# norm phases: write-through (sc0 sc1) stores so the barrier's L2 write-back finds less dirty data
# baseline (speedup 1.0000x reference)
.LBB0_330:
	s_or_b64 exec, exec, s[30:31]
	v_lshl_add_u32 v68, v1, 2, s7
	s_waitcnt lgkmcnt(0)
	s_barrier
	ds_read_b32 v68, v68 offset:256
	s_waitcnt vmcnt(8)
	v_mov_b32_e32 v98, v11
	v_mov_b32_e32 v99, v13
	s_addk_i32 s10, 0x80
	s_add_i32 s6, s6, s51
	s_waitcnt lgkmcnt(0)
	ds_bpermute_b32 v69, v89, v68
	s_waitcnt lgkmcnt(0)
	v_add_f32_e32 v96, v68, v69
	ds_bpermute_b32 v97, v90, v96
	v_lshl_add_u64 v[68:69], v[78:79], 0, s[28:29]
	s_waitcnt lgkmcnt(0)
	v_add_f32_e32 v100, v96, v97
	ds_bpermute_b32 v101, v91, v100
	v_mov_b32_e32 v96, v10
	v_mov_b32_e32 v97, v12
	s_waitcnt lgkmcnt(0)
	v_add_f32_e32 v100, v100, v101
	s_nop 0
	v_readlane_b32 s7, v100, 0
	v_readlane_b32 s28, v100, 1
	v_readlane_b32 s29, v100, 2
	v_fma_f32 v101, s7, v95, v92
	v_mul_f32_e32 v102, 0x4b800000, v101
	v_cmp_gt_f32_e32 vcc, s53, v101
	v_readlane_b32 s30, v100, 3
	v_readlane_b32 s31, v100, 4
	v_cndmask_b32_e32 v101, v101, v102, vcc
	v_rsq_f32_e32 v101, v101
	v_readlane_b32 s55, v100, 5
	v_readlane_b32 s58, v100, 6
	v_readlane_b32 s7, v100, 7
	v_mul_f32_e32 v100, 0x45800000, v101
	v_cndmask_b32_e32 v100, v101, v100, vcc
	v_pk_mul_f32 v[66:67], v[66:67], v[100:101] op_sel_hi:[1,0]
	v_pk_mul_f32 v[64:65], v[64:65], v[100:101] op_sel_hi:[1,0]
	v_pk_fma_f32 v[66:67], v[82:83], v[66:67], v[96:97]
	v_pk_fma_f32 v[64:65], v[80:81], v[64:65], v[98:99]
	v_and_b32_sdwa v100, v67, v94 dst_sel:DWORD dst_unused:UNUSED_PAD src0_sel:WORD_1 src1_sel:DWORD
	v_and_b32_sdwa v101, v66, v94 dst_sel:DWORD dst_unused:UNUSED_PAD src0_sel:WORD_1 src1_sel:DWORD
	v_add3_u32 v67, v67, v100, s52
	v_and_b32_sdwa v100, v65, v94 dst_sel:DWORD dst_unused:UNUSED_PAD src0_sel:WORD_1 src1_sel:DWORD
	v_add3_u32 v66, v66, v101, s52
	v_and_b32_sdwa v101, v64, v94 dst_sel:DWORD dst_unused:UNUSED_PAD src0_sel:WORD_1 src1_sel:DWORD
	v_add3_u32 v65, v65, v100, s52
	v_fma_f32 v100, s28, v95, v92
	v_add3_u32 v64, v64, v101, s52
	v_mul_f32_e32 v101, 0x4b800000, v100
	v_cmp_gt_f32_e32 vcc, s53, v100
	v_and_b32_e32 v65, 0xffff0000, v65
	v_and_b32_e32 v64, 0xffff0000, v64
	v_cndmask_b32_e32 v100, v100, v101, vcc
	v_rsq_f32_e32 v100, v100
	v_or_b32_sdwa v65, v65, v67 dst_sel:DWORD dst_unused:UNUSED_PAD src0_sel:DWORD src1_sel:WORD_1
	v_or_b32_sdwa v64, v64, v66 dst_sel:DWORD dst_unused:UNUSED_PAD src0_sel:DWORD src1_sel:WORD_1
	global_store_dwordx2 v[68:69], v[64:65], off sc0 sc1
	v_mul_f32_e32 v64, 0x45800000, v100
	v_cndmask_b32_e32 v64, v100, v64, vcc
	v_pk_mul_f32 v[62:63], v[62:63], v[64:65] op_sel_hi:[1,0]
	v_pk_mul_f32 v[60:61], v[60:61], v[64:65] op_sel_hi:[1,0]
	v_pk_fma_f32 v[62:63], v[82:83], v[62:63], v[96:97]
	v_pk_fma_f32 v[60:61], v[80:81], v[60:61], v[98:99]
	v_and_b32_sdwa v64, v63, v94 dst_sel:DWORD dst_unused:UNUSED_PAD src0_sel:WORD_1 src1_sel:DWORD
	v_and_b32_sdwa v65, v62, v94 dst_sel:DWORD dst_unused:UNUSED_PAD src0_sel:WORD_1 src1_sel:DWORD
	v_add3_u32 v63, v63, v64, s52
	v_and_b32_sdwa v64, v61, v94 dst_sel:DWORD dst_unused:UNUSED_PAD src0_sel:WORD_1 src1_sel:DWORD
	v_add3_u32 v62, v62, v65, s52
	v_and_b32_sdwa v65, v60, v94 dst_sel:DWORD dst_unused:UNUSED_PAD src0_sel:WORD_1 src1_sel:DWORD
	v_add3_u32 v61, v61, v64, s52
	v_fma_f32 v64, s29, v95, v92
	v_add3_u32 v60, v60, v65, s52
	v_mul_f32_e32 v65, 0x4b800000, v64
	v_cmp_gt_f32_e32 vcc, s53, v64
	v_and_b32_e32 v61, 0xffff0000, v61
	v_and_b32_e32 v60, 0xffff0000, v60
	v_cndmask_b32_e32 v64, v64, v65, vcc
	v_rsq_f32_e32 v64, v64
	v_lshl_add_u64 v[66:67], v[78:79], 0, s[26:27]
	v_or_b32_sdwa v61, v61, v63 dst_sel:DWORD dst_unused:UNUSED_PAD src0_sel:DWORD src1_sel:WORD_1
	v_or_b32_sdwa v60, v60, v62 dst_sel:DWORD dst_unused:UNUSED_PAD src0_sel:DWORD src1_sel:WORD_1
	global_store_dwordx2 v[66:67], v[60:61], off sc0 sc1
	v_mul_f32_e32 v60, 0x45800000, v64
	v_cndmask_b32_e32 v60, v64, v60, vcc
	v_pk_mul_f32 v[58:59], v[58:59], v[60:61] op_sel_hi:[1,0]
	v_pk_mul_f32 v[44:45], v[44:45], v[60:61] op_sel_hi:[1,0]
	v_pk_fma_f32 v[58:59], v[82:83], v[58:59], v[96:97]
	v_pk_fma_f32 v[44:45], v[80:81], v[44:45], v[98:99]
	v_and_b32_sdwa v60, v59, v94 dst_sel:DWORD dst_unused:UNUSED_PAD src0_sel:WORD_1 src1_sel:DWORD
	v_and_b32_sdwa v61, v58, v94 dst_sel:DWORD dst_unused:UNUSED_PAD src0_sel:WORD_1 src1_sel:DWORD
	v_add3_u32 v59, v59, v60, s52
	v_and_b32_sdwa v60, v45, v94 dst_sel:DWORD dst_unused:UNUSED_PAD src0_sel:WORD_1 src1_sel:DWORD
	v_add3_u32 v58, v58, v61, s52
	v_and_b32_sdwa v61, v44, v94 dst_sel:DWORD dst_unused:UNUSED_PAD src0_sel:WORD_1 src1_sel:DWORD
	v_add3_u32 v45, v45, v60, s52
	v_fma_f32 v60, s30, v95, v92
	v_add3_u32 v44, v44, v61, s52
	v_mul_f32_e32 v61, 0x4b800000, v60
	v_cmp_gt_f32_e32 vcc, s53, v60
	v_and_b32_e32 v45, 0xffff0000, v45
	v_and_b32_e32 v44, 0xffff0000, v44
	v_cndmask_b32_e32 v60, v60, v61, vcc
	v_rsq_f32_e32 v60, v60
	v_lshl_add_u64 v[62:63], v[78:79], 0, s[24:25]
	v_or_b32_sdwa v45, v45, v59 dst_sel:DWORD dst_unused:UNUSED_PAD src0_sel:DWORD src1_sel:WORD_1
	v_or_b32_sdwa v44, v44, v58 dst_sel:DWORD dst_unused:UNUSED_PAD src0_sel:DWORD src1_sel:WORD_1
	global_store_dwordx2 v[62:63], v[44:45], off sc0 sc1
	v_mul_f32_e32 v44, 0x45800000, v60
	v_cndmask_b32_e32 v44, v60, v44, vcc
	v_pk_mul_f32 v[42:43], v[42:43], v[44:45] op_sel_hi:[1,0]
	v_pk_mul_f32 v[24:25], v[24:25], v[44:45] op_sel_hi:[1,0]
	v_pk_fma_f32 v[42:43], v[82:83], v[42:43], v[96:97]
	v_pk_fma_f32 v[24:25], v[80:81], v[24:25], v[98:99]
	v_and_b32_sdwa v44, v43, v94 dst_sel:DWORD dst_unused:UNUSED_PAD src0_sel:WORD_1 src1_sel:DWORD
	v_and_b32_sdwa v45, v42, v94 dst_sel:DWORD dst_unused:UNUSED_PAD src0_sel:WORD_1 src1_sel:DWORD
	v_add3_u32 v43, v43, v44, s52
	v_and_b32_sdwa v44, v25, v94 dst_sel:DWORD dst_unused:UNUSED_PAD src0_sel:WORD_1 src1_sel:DWORD
	v_add3_u32 v42, v42, v45, s52
	v_and_b32_sdwa v45, v24, v94 dst_sel:DWORD dst_unused:UNUSED_PAD src0_sel:WORD_1 src1_sel:DWORD
	v_add3_u32 v25, v25, v44, s52
	v_fma_f32 v44, s31, v95, v92
	v_add3_u32 v24, v24, v45, s52
	v_mul_f32_e32 v45, 0x4b800000, v44
	v_cmp_gt_f32_e32 vcc, s53, v44
	v_and_b32_e32 v25, 0xffff0000, v25
	v_and_b32_e32 v24, 0xffff0000, v24
	v_cndmask_b32_e32 v44, v44, v45, vcc
	v_rsq_f32_e32 v44, v44
	v_lshl_add_u64 v[58:59], v[78:79], 0, s[22:23]
	v_or_b32_sdwa v25, v25, v43 dst_sel:DWORD dst_unused:UNUSED_PAD src0_sel:DWORD src1_sel:WORD_1
	v_or_b32_sdwa v24, v24, v42 dst_sel:DWORD dst_unused:UNUSED_PAD src0_sel:DWORD src1_sel:WORD_1
	global_store_dwordx2 v[58:59], v[24:25], off sc0 sc1
	v_mul_f32_e32 v24, 0x45800000, v44
	v_cndmask_b32_e32 v24, v44, v24, vcc
	v_pk_mul_f32 v[22:23], v[22:23], v[24:25] op_sel_hi:[1,0]
	v_pk_mul_f32 v[16:17], v[16:17], v[24:25] op_sel_hi:[1,0]
	v_pk_fma_f32 v[22:23], v[82:83], v[22:23], v[96:97]
	v_pk_fma_f32 v[16:17], v[80:81], v[16:17], v[98:99]
	v_and_b32_sdwa v24, v23, v94 dst_sel:DWORD dst_unused:UNUSED_PAD src0_sel:WORD_1 src1_sel:DWORD
	v_and_b32_sdwa v25, v22, v94 dst_sel:DWORD dst_unused:UNUSED_PAD src0_sel:WORD_1 src1_sel:DWORD
	v_add3_u32 v23, v23, v24, s52
	v_and_b32_sdwa v24, v17, v94 dst_sel:DWORD dst_unused:UNUSED_PAD src0_sel:WORD_1 src1_sel:DWORD
	v_add3_u32 v22, v22, v25, s52
	v_and_b32_sdwa v25, v16, v94 dst_sel:DWORD dst_unused:UNUSED_PAD src0_sel:WORD_1 src1_sel:DWORD
	v_add3_u32 v17, v17, v24, s52
	v_fma_f32 v24, s55, v95, v92
	v_add3_u32 v16, v16, v25, s52
	v_mul_f32_e32 v25, 0x4b800000, v24
	v_cmp_gt_f32_e32 vcc, s53, v24
	v_and_b32_e32 v17, 0xffff0000, v17
	v_and_b32_e32 v16, 0xffff0000, v16
	v_cndmask_b32_e32 v24, v24, v25, vcc
	v_rsq_f32_e32 v24, v24
	v_lshl_add_u64 v[42:43], v[78:79], 0, s[20:21]
	v_or_b32_sdwa v17, v17, v23 dst_sel:DWORD dst_unused:UNUSED_PAD src0_sel:DWORD src1_sel:WORD_1
	v_or_b32_sdwa v16, v16, v22 dst_sel:DWORD dst_unused:UNUSED_PAD src0_sel:DWORD src1_sel:WORD_1
	global_store_dwordx2 v[42:43], v[16:17], off sc0 sc1
	v_mul_f32_e32 v16, 0x45800000, v24
	v_cndmask_b32_e32 v16, v24, v16, vcc
	v_pk_mul_f32 v[14:15], v[14:15], v[16:17] op_sel_hi:[1,0]
	v_pk_mul_f32 v[8:9], v[8:9], v[16:17] op_sel_hi:[1,0]
	v_pk_fma_f32 v[14:15], v[82:83], v[14:15], v[96:97]
	v_pk_fma_f32 v[8:9], v[80:81], v[8:9], v[98:99]
	v_and_b32_sdwa v16, v15, v94 dst_sel:DWORD dst_unused:UNUSED_PAD src0_sel:WORD_1 src1_sel:DWORD
	v_and_b32_sdwa v17, v14, v94 dst_sel:DWORD dst_unused:UNUSED_PAD src0_sel:WORD_1 src1_sel:DWORD
	v_add3_u32 v15, v15, v16, s52
	v_and_b32_sdwa v16, v9, v94 dst_sel:DWORD dst_unused:UNUSED_PAD src0_sel:WORD_1 src1_sel:DWORD
	v_add3_u32 v14, v14, v17, s52
	v_and_b32_sdwa v17, v8, v94 dst_sel:DWORD dst_unused:UNUSED_PAD src0_sel:WORD_1 src1_sel:DWORD
	v_add3_u32 v9, v9, v16, s52
	v_fma_f32 v16, s58, v95, v92
	v_add3_u32 v8, v8, v17, s52
	v_mul_f32_e32 v17, 0x4b800000, v16
	v_cmp_gt_f32_e32 vcc, s53, v16
	v_and_b32_e32 v9, 0xffff0000, v9
	v_and_b32_e32 v8, 0xffff0000, v8
	v_cndmask_b32_e32 v16, v16, v17, vcc
	v_rsq_f32_e32 v16, v16
	v_lshl_add_u64 v[22:23], v[78:79], 0, s[18:19]
	v_or_b32_sdwa v9, v9, v15 dst_sel:DWORD dst_unused:UNUSED_PAD src0_sel:DWORD src1_sel:WORD_1
	v_or_b32_sdwa v8, v8, v14 dst_sel:DWORD dst_unused:UNUSED_PAD src0_sel:DWORD src1_sel:WORD_1
	global_store_dwordx2 v[22:23], v[8:9], off sc0 sc1
	v_mul_f32_e32 v8, 0x45800000, v16
	v_cndmask_b32_e32 v8, v16, v8, vcc
	v_pk_mul_f32 v[6:7], v[6:7], v[8:9] op_sel_hi:[1,0]
	v_pk_mul_f32 v[4:5], v[4:5], v[8:9] op_sel_hi:[1,0]
	v_pk_fma_f32 v[6:7], v[82:83], v[6:7], v[96:97]
	v_pk_fma_f32 v[4:5], v[80:81], v[4:5], v[98:99]
	v_and_b32_sdwa v8, v7, v94 dst_sel:DWORD dst_unused:UNUSED_PAD src0_sel:WORD_1 src1_sel:DWORD
	v_and_b32_sdwa v9, v6, v94 dst_sel:DWORD dst_unused:UNUSED_PAD src0_sel:WORD_1 src1_sel:DWORD
	v_add3_u32 v7, v7, v8, s52
	v_and_b32_sdwa v8, v5, v94 dst_sel:DWORD dst_unused:UNUSED_PAD src0_sel:WORD_1 src1_sel:DWORD
	v_add3_u32 v6, v6, v9, s52
	v_and_b32_sdwa v9, v4, v94 dst_sel:DWORD dst_unused:UNUSED_PAD src0_sel:WORD_1 src1_sel:DWORD
	v_add3_u32 v5, v5, v8, s52
	v_fma_f32 v8, s7, v95, v92
	v_add3_u32 v4, v4, v9, s52
	v_mul_f32_e32 v9, 0x4b800000, v8
	v_cmp_gt_f32_e32 vcc, s53, v8
	v_and_b32_e32 v5, 0xffff0000, v5
	v_and_b32_e32 v4, 0xffff0000, v4
	v_cndmask_b32_e32 v8, v8, v9, vcc
	v_rsq_f32_e32 v8, v8
	v_lshl_add_u64 v[14:15], v[78:79], 0, s[16:17]
	v_or_b32_sdwa v5, v5, v7 dst_sel:DWORD dst_unused:UNUSED_PAD src0_sel:DWORD src1_sel:WORD_1
	v_or_b32_sdwa v4, v4, v6 dst_sel:DWORD dst_unused:UNUSED_PAD src0_sel:DWORD src1_sel:WORD_1
	global_store_dwordx2 v[14:15], v[4:5], off sc0 sc1
	v_mul_f32_e32 v4, 0x45800000, v8
	v_cndmask_b32_e32 v4, v8, v4, vcc
	v_pk_mul_f32 v[2:3], v[2:3], v[4:5] op_sel_hi:[1,0]
	v_pk_mul_f32 v[4:5], v[84:85], v[4:5] op_sel_hi:[1,0]
	v_pk_fma_f32 v[2:3], v[82:83], v[2:3], v[96:97]
	v_pk_fma_f32 v[4:5], v[80:81], v[4:5], v[98:99]
	v_and_b32_sdwa v8, v3, v94 dst_sel:DWORD dst_unused:UNUSED_PAD src0_sel:WORD_1 src1_sel:DWORD
	v_and_b32_sdwa v9, v2, v94 dst_sel:DWORD dst_unused:UNUSED_PAD src0_sel:WORD_1 src1_sel:DWORD
	v_add3_u32 v2, v2, v9, s52
	v_add3_u32 v3, v3, v8, s52
	v_and_b32_sdwa v8, v5, v94 dst_sel:DWORD dst_unused:UNUSED_PAD src0_sel:WORD_1 src1_sel:DWORD
	v_and_b32_sdwa v9, v4, v94 dst_sel:DWORD dst_unused:UNUSED_PAD src0_sel:WORD_1 src1_sel:DWORD
	v_add3_u32 v5, v5, v8, s52
	v_add3_u32 v4, v4, v9, s52
	v_and_b32_e32 v5, 0xffff0000, v5
	v_and_b32_e32 v4, 0xffff0000, v4
	v_lshl_add_u64 v[6:7], v[78:79], 0, s[14:15]
	v_or_b32_sdwa v3, v5, v3 dst_sel:DWORD dst_unused:UNUSED_PAD src0_sel:DWORD src1_sel:WORD_1
	v_or_b32_sdwa v2, v4, v2 dst_sel:DWORD dst_unused:UNUSED_PAD src0_sel:DWORD src1_sel:WORD_1
	global_store_dwordx2 v[6:7], v[2:3], off sc0 sc1
	s_andn2_b64 vcc, exec, s[12:13]
	v_mov_b32_e32 v84, v55
	v_mov_b32_e32 v85, v57
	v_mov_b32_e32 v2, v54
	v_mov_b32_e32 v3, v56
	v_mov_b32_e32 v4, v51
	v_mov_b32_e32 v5, v53
	v_mov_b32_e32 v6, v50
	v_mov_b32_e32 v7, v52
	v_mov_b32_e32 v8, v47
	v_mov_b32_e32 v9, v49
	v_mov_b32_e32 v14, v46
	v_mov_b32_e32 v15, v48
	v_mov_b32_e32 v16, v39
	v_mov_b32_e32 v17, v41
	v_mov_b32_e32 v22, v38
	v_mov_b32_e32 v23, v40
	v_mov_b32_e32 v24, v35
	v_mov_b32_e32 v25, v37
	v_mov_b32_e32 v42, v34
	v_mov_b32_e32 v43, v36
	v_mov_b32_e32 v44, v31
	v_mov_b32_e32 v45, v33
	v_mov_b32_e32 v58, v30
	v_mov_b32_e32 v59, v32
	v_mov_b32_e32 v60, v27
	v_mov_b32_e32 v61, v29
	v_mov_b32_e32 v62, v26
	v_mov_b32_e32 v63, v28
	v_mov_b32_e32 v64, v19
	v_mov_b32_e32 v65, v21
	v_mov_b32_e32 v66, v18
	v_mov_b32_e32 v67, v20
	s_cbranch_vccz .LBB0_337

.LBB0_335:
	v_and_b32_sdwa v97, v66, v94 dst_sel:DWORD dst_unused:UNUSED_PAD src0_sel:WORD_1 src1_sel:DWORD
	s_add_i32 s14, s6, -7
	v_add3_u32 v98, v66, v97, s52
	v_and_b32_sdwa v97, v65, v94 dst_sel:DWORD dst_unused:UNUSED_PAD src0_sel:WORD_1 src1_sel:DWORD
	v_and_b32_sdwa v99, v64, v94 dst_sel:DWORD dst_unused:UNUSED_PAD src0_sel:WORD_1 src1_sel:DWORD
	s_ashr_i32 s15, s14, 31
	v_and_b32_sdwa v96, v67, v94 dst_sel:DWORD dst_unused:UNUSED_PAD src0_sel:WORD_1 src1_sel:DWORD
	v_add3_u32 v97, v65, v97, s52
	v_add3_u32 v99, v64, v99, s52
	s_lshl_b64 s[28:29], s[14:15], 12
	v_add3_u32 v96, v67, v96, s52
	v_and_b32_e32 v97, 0xffff0000, v97
	v_and_b32_e32 v99, 0xffff0000, v99
	v_lshl_add_u64 v[68:69], v[76:77], 0, s[28:29]
	v_or_b32_sdwa v97, v96, v97 dst_sel:DWORD dst_unused:UNUSED_PAD src0_sel:WORD_1 src1_sel:DWORD
	v_or_b32_sdwa v96, v98, v99 dst_sel:DWORD dst_unused:UNUSED_PAD src0_sel:WORD_1 src1_sel:DWORD
	global_store_dwordx2 v[68:69], v[96:97], off sc0 sc1
	v_and_b32_sdwa v97, v62, v94 dst_sel:DWORD dst_unused:UNUSED_PAD src0_sel:WORD_1 src1_sel:DWORD
	s_add_i32 s14, s6, -6
	v_add3_u32 v98, v62, v97, s52
	v_and_b32_sdwa v97, v61, v94 dst_sel:DWORD dst_unused:UNUSED_PAD src0_sel:WORD_1 src1_sel:DWORD
	v_and_b32_sdwa v99, v60, v94 dst_sel:DWORD dst_unused:UNUSED_PAD src0_sel:WORD_1 src1_sel:DWORD
	s_ashr_i32 s15, s14, 31
	v_and_b32_sdwa v96, v63, v94 dst_sel:DWORD dst_unused:UNUSED_PAD src0_sel:WORD_1 src1_sel:DWORD
	v_add3_u32 v97, v61, v97, s52
	v_add3_u32 v99, v60, v99, s52
	s_lshl_b64 s[26:27], s[14:15], 12
	v_add3_u32 v96, v63, v96, s52
	v_and_b32_e32 v97, 0xffff0000, v97
	v_and_b32_e32 v99, 0xffff0000, v99
	v_lshl_add_u64 v[68:69], v[76:77], 0, s[26:27]
	v_or_b32_sdwa v97, v96, v97 dst_sel:DWORD dst_unused:UNUSED_PAD src0_sel:WORD_1 src1_sel:DWORD
	v_or_b32_sdwa v96, v98, v99 dst_sel:DWORD dst_unused:UNUSED_PAD src0_sel:WORD_1 src1_sel:DWORD
	global_store_dwordx2 v[68:69], v[96:97], off sc0 sc1
	v_and_b32_sdwa v97, v58, v94 dst_sel:DWORD dst_unused:UNUSED_PAD src0_sel:WORD_1 src1_sel:DWORD
	s_add_i32 s14, s6, -5
	v_add3_u32 v98, v58, v97, s52
	v_and_b32_sdwa v97, v45, v94 dst_sel:DWORD dst_unused:UNUSED_PAD src0_sel:WORD_1 src1_sel:DWORD
	v_and_b32_sdwa v99, v44, v94 dst_sel:DWORD dst_unused:UNUSED_PAD src0_sel:WORD_1 src1_sel:DWORD
	s_ashr_i32 s15, s14, 31
	v_and_b32_sdwa v96, v59, v94 dst_sel:DWORD dst_unused:UNUSED_PAD src0_sel:WORD_1 src1_sel:DWORD
	v_add3_u32 v97, v45, v97, s52
	v_add3_u32 v99, v44, v99, s52
	s_lshl_b64 s[24:25], s[14:15], 12
	v_add3_u32 v96, v59, v96, s52
	v_and_b32_e32 v97, 0xffff0000, v97
	v_and_b32_e32 v99, 0xffff0000, v99
	v_lshl_add_u64 v[68:69], v[76:77], 0, s[24:25]
	v_or_b32_sdwa v97, v96, v97 dst_sel:DWORD dst_unused:UNUSED_PAD src0_sel:WORD_1 src1_sel:DWORD
	v_or_b32_sdwa v96, v98, v99 dst_sel:DWORD dst_unused:UNUSED_PAD src0_sel:WORD_1 src1_sel:DWORD
	global_store_dwordx2 v[68:69], v[96:97], off sc0 sc1
	v_and_b32_sdwa v97, v42, v94 dst_sel:DWORD dst_unused:UNUSED_PAD src0_sel:WORD_1 src1_sel:DWORD
	s_add_i32 s14, s6, -4
	v_add3_u32 v98, v42, v97, s52
	v_and_b32_sdwa v97, v25, v94 dst_sel:DWORD dst_unused:UNUSED_PAD src0_sel:WORD_1 src1_sel:DWORD
	v_and_b32_sdwa v99, v24, v94 dst_sel:DWORD dst_unused:UNUSED_PAD src0_sel:WORD_1 src1_sel:DWORD
	s_ashr_i32 s15, s14, 31
	v_and_b32_sdwa v96, v43, v94 dst_sel:DWORD dst_unused:UNUSED_PAD src0_sel:WORD_1 src1_sel:DWORD
	v_add3_u32 v97, v25, v97, s52
	v_add3_u32 v99, v24, v99, s52
	s_lshl_b64 s[22:23], s[14:15], 12
	v_add3_u32 v96, v43, v96, s52
	v_and_b32_e32 v97, 0xffff0000, v97
	v_and_b32_e32 v99, 0xffff0000, v99
	v_lshl_add_u64 v[68:69], v[76:77], 0, s[22:23]
	v_or_b32_sdwa v97, v96, v97 dst_sel:DWORD dst_unused:UNUSED_PAD src0_sel:WORD_1 src1_sel:DWORD
	v_or_b32_sdwa v96, v98, v99 dst_sel:DWORD dst_unused:UNUSED_PAD src0_sel:WORD_1 src1_sel:DWORD
	global_store_dwordx2 v[68:69], v[96:97], off sc0 sc1
	v_and_b32_sdwa v97, v22, v94 dst_sel:DWORD dst_unused:UNUSED_PAD src0_sel:WORD_1 src1_sel:DWORD
	s_add_i32 s14, s6, -3
	v_add3_u32 v98, v22, v97, s52
	v_and_b32_sdwa v97, v17, v94 dst_sel:DWORD dst_unused:UNUSED_PAD src0_sel:WORD_1 src1_sel:DWORD
	v_and_b32_sdwa v99, v16, v94 dst_sel:DWORD dst_unused:UNUSED_PAD src0_sel:WORD_1 src1_sel:DWORD
	s_ashr_i32 s15, s14, 31
	v_and_b32_sdwa v96, v23, v94 dst_sel:DWORD dst_unused:UNUSED_PAD src0_sel:WORD_1 src1_sel:DWORD
	v_add3_u32 v97, v17, v97, s52
	v_add3_u32 v99, v16, v99, s52
	s_lshl_b64 s[20:21], s[14:15], 12
	v_add3_u32 v96, v23, v96, s52
	v_and_b32_e32 v97, 0xffff0000, v97
	v_and_b32_e32 v99, 0xffff0000, v99
	v_lshl_add_u64 v[68:69], v[76:77], 0, s[20:21]
	v_or_b32_sdwa v97, v96, v97 dst_sel:DWORD dst_unused:UNUSED_PAD src0_sel:WORD_1 src1_sel:DWORD
	v_or_b32_sdwa v96, v98, v99 dst_sel:DWORD dst_unused:UNUSED_PAD src0_sel:WORD_1 src1_sel:DWORD
	global_store_dwordx2 v[68:69], v[96:97], off sc0 sc1
	v_and_b32_sdwa v97, v14, v94 dst_sel:DWORD dst_unused:UNUSED_PAD src0_sel:WORD_1 src1_sel:DWORD
	s_add_i32 s14, s6, -2
	v_add3_u32 v98, v14, v97, s52
	v_and_b32_sdwa v97, v9, v94 dst_sel:DWORD dst_unused:UNUSED_PAD src0_sel:WORD_1 src1_sel:DWORD
	v_and_b32_sdwa v99, v8, v94 dst_sel:DWORD dst_unused:UNUSED_PAD src0_sel:WORD_1 src1_sel:DWORD
	s_ashr_i32 s15, s14, 31
	v_and_b32_sdwa v96, v15, v94 dst_sel:DWORD dst_unused:UNUSED_PAD src0_sel:WORD_1 src1_sel:DWORD
	v_add3_u32 v97, v9, v97, s52
	v_add3_u32 v99, v8, v99, s52
	s_lshl_b64 s[18:19], s[14:15], 12
	v_add3_u32 v96, v15, v96, s52
	v_and_b32_e32 v97, 0xffff0000, v97
	v_and_b32_e32 v99, 0xffff0000, v99
	v_lshl_add_u64 v[68:69], v[76:77], 0, s[18:19]
	v_or_b32_sdwa v97, v96, v97 dst_sel:DWORD dst_unused:UNUSED_PAD src0_sel:WORD_1 src1_sel:DWORD
	v_or_b32_sdwa v96, v98, v99 dst_sel:DWORD dst_unused:UNUSED_PAD src0_sel:WORD_1 src1_sel:DWORD
	global_store_dwordx2 v[68:69], v[96:97], off sc0 sc1
	v_and_b32_sdwa v97, v6, v94 dst_sel:DWORD dst_unused:UNUSED_PAD src0_sel:WORD_1 src1_sel:DWORD
	s_add_i32 s14, s6, -1
	v_add3_u32 v98, v6, v97, s52
	v_and_b32_sdwa v97, v5, v94 dst_sel:DWORD dst_unused:UNUSED_PAD src0_sel:WORD_1 src1_sel:DWORD
	v_and_b32_sdwa v99, v4, v94 dst_sel:DWORD dst_unused:UNUSED_PAD src0_sel:WORD_1 src1_sel:DWORD
	s_ashr_i32 s15, s14, 31
	v_and_b32_sdwa v96, v7, v94 dst_sel:DWORD dst_unused:UNUSED_PAD src0_sel:WORD_1 src1_sel:DWORD
	v_add3_u32 v97, v5, v97, s52
	v_add3_u32 v99, v4, v99, s52
	s_lshl_b64 s[16:17], s[14:15], 12
	v_add3_u32 v96, v7, v96, s52
	v_and_b32_e32 v97, 0xffff0000, v97
	v_and_b32_e32 v99, 0xffff0000, v99
	v_lshl_add_u64 v[68:69], v[76:77], 0, s[16:17]
	v_or_b32_sdwa v97, v96, v97 dst_sel:DWORD dst_unused:UNUSED_PAD src0_sel:WORD_1 src1_sel:DWORD
	v_or_b32_sdwa v96, v98, v99 dst_sel:DWORD dst_unused:UNUSED_PAD src0_sel:WORD_1 src1_sel:DWORD
	global_store_dwordx2 v[68:69], v[96:97], off sc0 sc1
	v_pk_mul_f32 v[68:69], v[66:67], v[66:67]
	v_pk_mul_f32 v[98:99], v[64:65], v[64:65]
	s_ashr_i32 s7, s6, 31
	v_add_f32_e32 v68, v98, v68
	v_add_f32_e32 v68, v69, v68
	v_add_f32_e32 v100, v99, v68
	v_pk_mul_f32 v[68:69], v[62:63], v[62:63]
	v_pk_mul_f32 v[98:99], v[60:61], v[60:61]
	s_lshl_b64 s[14:15], s[6:7], 12
	v_add_f32_e32 v68, v98, v68
	v_add_f32_e32 v68, v69, v68
	v_add_f32_e32 v101, v99, v68
	v_pk_mul_f32 v[68:69], v[58:59], v[58:59]
	v_pk_mul_f32 v[98:99], v[44:45], v[44:45]
	s_and_b32 s7, s10, 0x80
	v_add_f32_e32 v68, v98, v68
	v_add_f32_e32 v68, v69, v68
	v_add_f32_e32 v102, v99, v68
	v_pk_mul_f32 v[68:69], v[42:43], v[42:43]
	v_pk_mul_f32 v[98:99], v[24:25], v[24:25]
	s_lshl_b32 s7, s7, 2
	v_add_f32_e32 v68, v98, v68
	v_add_f32_e32 v68, v69, v68
	v_add_f32_e32 v103, v99, v68
	v_pk_mul_f32 v[68:69], v[22:23], v[22:23]
	v_pk_mul_f32 v[98:99], v[16:17], v[16:17]
	v_lshl_add_u64 v[96:97], v[76:77], 0, s[14:15]
	v_add_f32_e32 v68, v98, v68
	v_add_f32_e32 v68, v69, v68
	v_add_f32_e32 v104, v99, v68
	v_pk_mul_f32 v[68:69], v[14:15], v[14:15]
	v_pk_mul_f32 v[98:99], v[8:9], v[8:9]
	v_cndmask_b32_e64 v107, v100, v104, s[0:1]
	v_add_f32_e32 v68, v98, v68
	v_add_f32_e32 v68, v69, v68
	v_add_f32_e32 v105, v99, v68
	v_pk_mul_f32 v[68:69], v[6:7], v[6:7]
	v_pk_mul_f32 v[98:99], v[4:5], v[4:5]
	ds_bpermute_b32 v107, v86, v107
	v_add_f32_e32 v68, v98, v68
	v_add_f32_e32 v68, v69, v68
	v_add_f32_e32 v106, v99, v68
	v_pk_mul_f32 v[68:69], v[2:3], v[2:3]
	v_pk_mul_f32 v[98:99], v[84:85], v[84:85]
	s_add_i32 s7, s7, 0
	v_add_f32_e32 v68, v98, v68
	v_add_f32_e32 v68, v69, v68
	v_add_f32_e32 v68, v99, v68
	v_cndmask_b32_e64 v99, v101, v105, s[0:1]
	v_cndmask_b32_e64 v69, v104, v100, s[0:1]
	v_cndmask_b32_e64 v98, v105, v101, s[0:1]
	ds_bpermute_b32 v99, v86, v99
	v_cndmask_b32_e64 v100, v102, v106, s[0:1]
	v_cndmask_b32_e64 v101, v103, v68, s[0:1]
	ds_bpermute_b32 v100, v86, v100
	ds_bpermute_b32 v101, v86, v101
	s_waitcnt lgkmcnt(2)
	v_add_f32_e32 v98, v98, v99
	v_cndmask_b32_e64 v99, v106, v102, s[0:1]
	v_cndmask_b32_e64 v68, v68, v103, s[0:1]
	v_add_f32_e32 v69, v69, v107
	s_waitcnt lgkmcnt(1)
	v_add_f32_e32 v99, v99, v100
	s_waitcnt lgkmcnt(0)
	v_add_f32_e32 v68, v68, v101
	v_cndmask_b32_e64 v100, v69, v99, s[8:9]
	v_cndmask_b32_e64 v101, v98, v68, s[8:9]
	ds_bpermute_b32 v100, v87, v100
	ds_bpermute_b32 v101, v87, v101
	v_cndmask_b32_e64 v69, v99, v69, s[8:9]
	v_cndmask_b32_e64 v68, v68, v98, s[8:9]
	v_and_b32_sdwa v102, v3, v94 dst_sel:DWORD dst_unused:UNUSED_PAD src0_sel:WORD_1 src1_sel:DWORD
	s_waitcnt lgkmcnt(1)
	v_add_f32_e32 v69, v69, v100
	s_waitcnt lgkmcnt(0)
	v_add_f32_e32 v68, v68, v101
	v_cndmask_b32_e64 v98, v69, v68, s[4:5]
	ds_bpermute_b32 v98, v88, v98
	v_cndmask_b32_e64 v68, v68, v69, s[4:5]
	v_and_b32_sdwa v101, v84, v94 dst_sel:DWORD dst_unused:UNUSED_PAD src0_sel:WORD_1 src1_sel:DWORD
	v_and_b32_sdwa v99, v2, v94 dst_sel:DWORD dst_unused:UNUSED_PAD src0_sel:WORD_1 src1_sel:DWORD
	v_add3_u32 v101, v84, v101, s52
	s_waitcnt lgkmcnt(0)
	v_add_f32_e32 v68, v68, v98
	ds_bpermute_b32 v69, v89, v68
	v_and_b32_sdwa v98, v85, v94 dst_sel:DWORD dst_unused:UNUSED_PAD src0_sel:WORD_1 src1_sel:DWORD
	v_add3_u32 v98, v85, v98, s52
	v_add3_u32 v100, v2, v99, s52
	v_add3_u32 v99, v3, v102, s52
	s_waitcnt lgkmcnt(0)
	v_add_f32_e32 v68, v68, v69
	ds_bpermute_b32 v69, v90, v68
	v_and_b32_e32 v98, 0xffff0000, v98
	v_and_b32_e32 v101, 0xffff0000, v101
	v_or_b32_sdwa v99, v99, v98 dst_sel:DWORD dst_unused:UNUSED_PAD src0_sel:WORD_1 src1_sel:DWORD
	v_or_b32_sdwa v98, v100, v101 dst_sel:DWORD dst_unused:UNUSED_PAD src0_sel:WORD_1 src1_sel:DWORD
	s_waitcnt lgkmcnt(0)
	v_add_f32_e32 v68, v68, v69
	ds_bpermute_b32 v69, v91, v68
	global_store_dwordx2 v[96:97], v[98:99], off sc0 sc1
	s_and_saveexec_b64 s[30:31], s[34:35]
	s_cbranch_execz .LBB0_330
	s_add_i32 s55, s7, s49
	v_lshl_add_u32 v96, v1, 2, s55
	s_waitcnt lgkmcnt(0)
	v_add_f32_e32 v68, v68, v69
	ds_write_b32 v96, v68 offset:256
	s_branch .LBB0_330

.LBB0_1149:
	s_or_b64 exec, exec, s[34:35]
	s_waitcnt lgkmcnt(0)
	s_barrier
	ds_read_b32 v2, v2 offset:256
	s_mov_b32 s2, 0x800000
	v_lshl_add_u64 v[102:103], v[28:29], 0, s[26:27]
	v_mov_b32_e32 v89, v6
	v_mov_b32_e32 v104, v5
	s_waitcnt lgkmcnt(0)
	ds_bpermute_b32 v88, v149, v2
	v_mov_b32_e32 v105, v7
	s_addk_i32 s48, 0x80
	s_waitcnt lgkmcnt(0)
	v_add_f32_e32 v2, v2, v88
	ds_bpermute_b32 v88, v150, v2
	s_waitcnt lgkmcnt(0)
	v_add_f32_e32 v2, v2, v88
	ds_bpermute_b32 v106, v151, v2
	v_mov_b32_e32 v88, v4
	s_waitcnt lgkmcnt(0)
	v_add_f32_e32 v2, v2, v106
	s_nop 0
	v_readlane_b32 s7, v2, 0
	v_readlane_b32 s26, v2, 1
	v_readlane_b32 s27, v2, 2
	v_fma_f32 v106, s7, v206, v203
	v_mul_f32_e32 v107, 0x4b800000, v106
	v_cmp_gt_f32_e32 vcc, s2, v106
	v_readlane_b32 s28, v2, 3
	v_readlane_b32 s34, v2, 4
	v_cndmask_b32_e32 v106, v106, v107, vcc
	v_rsq_f32_e32 v106, v106
	v_readlane_b32 s35, v2, 5
	v_readlane_b32 s51, v2, 6
	v_readlane_b32 s7, v2, 7
	v_mul_f32_e32 v2, 0x45800000, v106
	v_cndmask_b32_e32 v2, v106, v2, vcc
	v_pk_mul_f32 v[72:73], v[72:73], v[2:3] op_sel_hi:[1,0]
	v_pk_mul_f32 v[12:13], v[12:13], v[2:3] op_sel_hi:[1,0]
	v_pk_fma_f32 v[72:73], v[52:53], v[72:73], v[88:89]
	v_pk_fma_f32 v[12:13], v[54:55], v[12:13], v[104:105]
	v_and_b32_sdwa v2, v73, v202 dst_sel:DWORD dst_unused:UNUSED_PAD src0_sel:WORD_1 src1_sel:DWORD
	v_and_b32_sdwa v106, v72, v202 dst_sel:DWORD dst_unused:UNUSED_PAD src0_sel:WORD_1 src1_sel:DWORD
	v_add3_u32 v2, v73, v2, s5
	v_and_b32_sdwa v73, v13, v202 dst_sel:DWORD dst_unused:UNUSED_PAD src0_sel:WORD_1 src1_sel:DWORD
	v_add3_u32 v72, v72, v106, s5
	v_and_b32_sdwa v106, v12, v202 dst_sel:DWORD dst_unused:UNUSED_PAD src0_sel:WORD_1 src1_sel:DWORD
	v_add3_u32 v13, v13, v73, s5
	v_fma_f32 v73, s26, v206, v203
	v_add3_u32 v12, v12, v106, s5
	v_mul_f32_e32 v106, 0x4b800000, v73
	v_cmp_gt_f32_e32 vcc, s2, v73
	v_and_b32_e32 v13, 0xffff0000, v13
	v_or_b32_sdwa v13, v13, v2 dst_sel:DWORD dst_unused:UNUSED_PAD src0_sel:DWORD src1_sel:WORD_1
	v_cndmask_b32_e32 v73, v73, v106, vcc
	v_rsq_f32_e32 v73, v73
	v_and_b32_e32 v12, 0xffff0000, v12
	v_or_b32_sdwa v12, v12, v72 dst_sel:DWORD dst_unused:UNUSED_PAD src0_sel:DWORD src1_sel:WORD_1
	global_store_dwordx2 v[102:103], v[12:13], off sc0 sc1
	v_mul_f32_e32 v2, 0x45800000, v73
	v_cndmask_b32_e32 v2, v73, v2, vcc
	v_pk_mul_f32 v[72:73], v[74:75], v[2:3] op_sel_hi:[1,0]
	v_pk_mul_f32 v[74:75], v[76:77], v[2:3] op_sel_hi:[1,0]
	v_pk_fma_f32 v[72:73], v[52:53], v[72:73], v[88:89]
	v_pk_fma_f32 v[74:75], v[54:55], v[74:75], v[104:105]
	v_and_b32_sdwa v2, v73, v202 dst_sel:DWORD dst_unused:UNUSED_PAD src0_sel:WORD_1 src1_sel:DWORD
	v_and_b32_sdwa v76, v72, v202 dst_sel:DWORD dst_unused:UNUSED_PAD src0_sel:WORD_1 src1_sel:DWORD
	v_add3_u32 v2, v73, v2, s5
	v_and_b32_sdwa v73, v75, v202 dst_sel:DWORD dst_unused:UNUSED_PAD src0_sel:WORD_1 src1_sel:DWORD
	v_add3_u32 v72, v72, v76, s5
	v_and_b32_sdwa v76, v74, v202 dst_sel:DWORD dst_unused:UNUSED_PAD src0_sel:WORD_1 src1_sel:DWORD
	v_add3_u32 v73, v75, v73, s5
	v_fma_f32 v75, s27, v206, v203
	v_add3_u32 v74, v74, v76, s5
	v_mul_f32_e32 v76, 0x4b800000, v75
	v_cmp_gt_f32_e32 vcc, s2, v75
	v_and_b32_e32 v73, 0xffff0000, v73
	v_and_b32_e32 v74, 0xffff0000, v74
	v_cndmask_b32_e32 v75, v75, v76, vcc
	v_rsq_f32_e32 v75, v75
	v_or_b32_sdwa v73, v73, v2 dst_sel:DWORD dst_unused:UNUSED_PAD src0_sel:DWORD src1_sel:WORD_1
	v_lshl_add_u64 v[12:13], v[28:29], 0, s[24:25]
	v_or_b32_sdwa v72, v74, v72 dst_sel:DWORD dst_unused:UNUSED_PAD src0_sel:DWORD src1_sel:WORD_1
	v_mul_f32_e32 v2, 0x45800000, v75
	v_cndmask_b32_e32 v2, v75, v2, vcc
	global_store_dwordx2 v[12:13], v[72:73], off sc0 sc1
	v_pk_mul_f32 v[72:73], v[78:79], v[2:3] op_sel_hi:[1,0]
	v_pk_mul_f32 v[74:75], v[80:81], v[2:3] op_sel_hi:[1,0]
	v_pk_fma_f32 v[72:73], v[52:53], v[72:73], v[88:89]
	v_pk_fma_f32 v[74:75], v[54:55], v[74:75], v[104:105]
	v_and_b32_sdwa v2, v73, v202 dst_sel:DWORD dst_unused:UNUSED_PAD src0_sel:WORD_1 src1_sel:DWORD
	v_and_b32_sdwa v76, v72, v202 dst_sel:DWORD dst_unused:UNUSED_PAD src0_sel:WORD_1 src1_sel:DWORD
	v_add3_u32 v2, v73, v2, s5
	v_and_b32_sdwa v73, v75, v202 dst_sel:DWORD dst_unused:UNUSED_PAD src0_sel:WORD_1 src1_sel:DWORD
	v_add3_u32 v72, v72, v76, s5
	v_and_b32_sdwa v76, v74, v202 dst_sel:DWORD dst_unused:UNUSED_PAD src0_sel:WORD_1 src1_sel:DWORD
	v_add3_u32 v73, v75, v73, s5
	v_fma_f32 v75, s28, v206, v203
	v_add3_u32 v74, v74, v76, s5
	v_mul_f32_e32 v76, 0x4b800000, v75
	v_cmp_gt_f32_e32 vcc, s2, v75
	v_and_b32_e32 v73, 0xffff0000, v73
	v_and_b32_e32 v74, 0xffff0000, v74
	v_cndmask_b32_e32 v75, v75, v76, vcc
	v_rsq_f32_e32 v75, v75
	v_or_b32_sdwa v73, v73, v2 dst_sel:DWORD dst_unused:UNUSED_PAD src0_sel:DWORD src1_sel:WORD_1
	v_lshl_add_u64 v[12:13], v[28:29], 0, s[20:21]
	v_or_b32_sdwa v72, v74, v72 dst_sel:DWORD dst_unused:UNUSED_PAD src0_sel:DWORD src1_sel:WORD_1
	v_mul_f32_e32 v2, 0x45800000, v75
	v_cndmask_b32_e32 v2, v75, v2, vcc
	global_store_dwordx2 v[12:13], v[72:73], off sc0 sc1
	v_pk_mul_f32 v[72:73], v[82:83], v[2:3] op_sel_hi:[1,0]
	v_pk_mul_f32 v[74:75], v[84:85], v[2:3] op_sel_hi:[1,0]
	v_pk_fma_f32 v[72:73], v[52:53], v[72:73], v[88:89]
	v_pk_fma_f32 v[74:75], v[54:55], v[74:75], v[104:105]
	v_and_b32_sdwa v2, v73, v202 dst_sel:DWORD dst_unused:UNUSED_PAD src0_sel:WORD_1 src1_sel:DWORD
	v_and_b32_sdwa v76, v72, v202 dst_sel:DWORD dst_unused:UNUSED_PAD src0_sel:WORD_1 src1_sel:DWORD
	v_add3_u32 v2, v73, v2, s5
	v_and_b32_sdwa v73, v75, v202 dst_sel:DWORD dst_unused:UNUSED_PAD src0_sel:WORD_1 src1_sel:DWORD
	v_add3_u32 v72, v72, v76, s5
	v_and_b32_sdwa v76, v74, v202 dst_sel:DWORD dst_unused:UNUSED_PAD src0_sel:WORD_1 src1_sel:DWORD
	v_add3_u32 v73, v75, v73, s5
	v_fma_f32 v75, s34, v206, v203
	v_add3_u32 v74, v74, v76, s5
	v_mul_f32_e32 v76, 0x4b800000, v75
	v_cmp_gt_f32_e32 vcc, s2, v75
	v_and_b32_e32 v73, 0xffff0000, v73
	v_and_b32_e32 v74, 0xffff0000, v74
	v_cndmask_b32_e32 v75, v75, v76, vcc
	v_rsq_f32_e32 v75, v75
	v_or_b32_sdwa v73, v73, v2 dst_sel:DWORD dst_unused:UNUSED_PAD src0_sel:DWORD src1_sel:WORD_1
	v_lshl_add_u64 v[12:13], v[28:29], 0, s[18:19]
	v_or_b32_sdwa v72, v74, v72 dst_sel:DWORD dst_unused:UNUSED_PAD src0_sel:DWORD src1_sel:WORD_1
	v_mul_f32_e32 v2, 0x45800000, v75
	v_cndmask_b32_e32 v2, v75, v2, vcc
	global_store_dwordx2 v[12:13], v[72:73], off sc0 sc1
	v_pk_mul_f32 v[72:73], v[86:87], v[2:3] op_sel_hi:[1,0]
	v_pk_mul_f32 v[74:75], v[96:97], v[2:3] op_sel_hi:[1,0]
	v_pk_fma_f32 v[72:73], v[52:53], v[72:73], v[88:89]
	v_pk_fma_f32 v[74:75], v[54:55], v[74:75], v[104:105]
	v_and_b32_sdwa v2, v73, v202 dst_sel:DWORD dst_unused:UNUSED_PAD src0_sel:WORD_1 src1_sel:DWORD
	v_and_b32_sdwa v76, v72, v202 dst_sel:DWORD dst_unused:UNUSED_PAD src0_sel:WORD_1 src1_sel:DWORD
	v_add3_u32 v2, v73, v2, s5
	v_and_b32_sdwa v73, v75, v202 dst_sel:DWORD dst_unused:UNUSED_PAD src0_sel:WORD_1 src1_sel:DWORD
	v_add3_u32 v72, v72, v76, s5
	v_and_b32_sdwa v76, v74, v202 dst_sel:DWORD dst_unused:UNUSED_PAD src0_sel:WORD_1 src1_sel:DWORD
	v_add3_u32 v73, v75, v73, s5
	v_fma_f32 v75, s35, v206, v203
	v_add3_u32 v74, v74, v76, s5
	v_mul_f32_e32 v76, 0x4b800000, v75
	v_cmp_gt_f32_e32 vcc, s2, v75
	v_and_b32_e32 v73, 0xffff0000, v73
	v_and_b32_e32 v74, 0xffff0000, v74
	v_cndmask_b32_e32 v75, v75, v76, vcc
	v_rsq_f32_e32 v75, v75
	v_or_b32_sdwa v73, v73, v2 dst_sel:DWORD dst_unused:UNUSED_PAD src0_sel:DWORD src1_sel:WORD_1
	v_lshl_add_u64 v[12:13], v[28:29], 0, s[16:17]
	v_or_b32_sdwa v72, v74, v72 dst_sel:DWORD dst_unused:UNUSED_PAD src0_sel:DWORD src1_sel:WORD_1
	v_mul_f32_e32 v2, 0x45800000, v75
	v_cndmask_b32_e32 v2, v75, v2, vcc
	global_store_dwordx2 v[12:13], v[72:73], off sc0 sc1
	v_pk_mul_f32 v[72:73], v[100:101], v[2:3] op_sel_hi:[1,0]
	v_pk_mul_f32 v[74:75], v[94:95], v[2:3] op_sel_hi:[1,0]
	v_pk_fma_f32 v[72:73], v[52:53], v[72:73], v[88:89]
	v_pk_fma_f32 v[74:75], v[54:55], v[74:75], v[104:105]
	v_and_b32_sdwa v2, v73, v202 dst_sel:DWORD dst_unused:UNUSED_PAD src0_sel:WORD_1 src1_sel:DWORD
	v_and_b32_sdwa v76, v72, v202 dst_sel:DWORD dst_unused:UNUSED_PAD src0_sel:WORD_1 src1_sel:DWORD
	v_add3_u32 v2, v73, v2, s5
	v_and_b32_sdwa v73, v75, v202 dst_sel:DWORD dst_unused:UNUSED_PAD src0_sel:WORD_1 src1_sel:DWORD
	v_add3_u32 v72, v72, v76, s5
	v_and_b32_sdwa v76, v74, v202 dst_sel:DWORD dst_unused:UNUSED_PAD src0_sel:WORD_1 src1_sel:DWORD
	v_add3_u32 v73, v75, v73, s5
	v_fma_f32 v75, s51, v206, v203
	v_add3_u32 v74, v74, v76, s5
	v_mul_f32_e32 v76, 0x4b800000, v75
	v_cmp_gt_f32_e32 vcc, s2, v75
	v_and_b32_e32 v73, 0xffff0000, v73
	v_and_b32_e32 v74, 0xffff0000, v74
	v_cndmask_b32_e32 v75, v75, v76, vcc
	v_rsq_f32_e32 v75, v75
	v_or_b32_sdwa v73, v73, v2 dst_sel:DWORD dst_unused:UNUSED_PAD src0_sel:DWORD src1_sel:WORD_1
	v_lshl_add_u64 v[12:13], v[28:29], 0, s[14:15]
	v_or_b32_sdwa v72, v74, v72 dst_sel:DWORD dst_unused:UNUSED_PAD src0_sel:DWORD src1_sel:WORD_1
	v_mul_f32_e32 v2, 0x45800000, v75
	v_cndmask_b32_e32 v2, v75, v2, vcc
	global_store_dwordx2 v[12:13], v[72:73], off sc0 sc1
	v_pk_mul_f32 v[72:73], v[98:99], v[2:3] op_sel_hi:[1,0]
	v_pk_mul_f32 v[74:75], v[90:91], v[2:3] op_sel_hi:[1,0]
	v_pk_fma_f32 v[72:73], v[52:53], v[72:73], v[88:89]
	v_pk_fma_f32 v[74:75], v[54:55], v[74:75], v[104:105]
	v_and_b32_sdwa v2, v73, v202 dst_sel:DWORD dst_unused:UNUSED_PAD src0_sel:WORD_1 src1_sel:DWORD
	v_and_b32_sdwa v76, v72, v202 dst_sel:DWORD dst_unused:UNUSED_PAD src0_sel:WORD_1 src1_sel:DWORD
	v_add3_u32 v2, v73, v2, s5
	v_and_b32_sdwa v73, v75, v202 dst_sel:DWORD dst_unused:UNUSED_PAD src0_sel:WORD_1 src1_sel:DWORD
	v_add3_u32 v72, v72, v76, s5
	v_and_b32_sdwa v76, v74, v202 dst_sel:DWORD dst_unused:UNUSED_PAD src0_sel:WORD_1 src1_sel:DWORD
	v_add3_u32 v73, v75, v73, s5
	v_fma_f32 v75, s7, v206, v203
	v_add3_u32 v74, v74, v76, s5
	v_mul_f32_e32 v76, 0x4b800000, v75
	v_cmp_gt_f32_e32 vcc, s2, v75
	v_and_b32_e32 v73, 0xffff0000, v73
	v_and_b32_e32 v74, 0xffff0000, v74
	v_cndmask_b32_e32 v75, v75, v76, vcc
	v_rsq_f32_e32 v75, v75
	v_or_b32_sdwa v73, v73, v2 dst_sel:DWORD dst_unused:UNUSED_PAD src0_sel:DWORD src1_sel:WORD_1
	v_lshl_add_u64 v[12:13], v[28:29], 0, s[12:13]
	v_or_b32_sdwa v72, v74, v72 dst_sel:DWORD dst_unused:UNUSED_PAD src0_sel:DWORD src1_sel:WORD_1
	v_mul_f32_e32 v2, 0x45800000, v75
	v_cndmask_b32_e32 v2, v75, v2, vcc
	global_store_dwordx2 v[12:13], v[72:73], off sc0 sc1
	v_pk_mul_f32 v[72:73], v[92:93], v[2:3] op_sel_hi:[1,0]
	v_pk_mul_f32 v[14:15], v[14:15], v[2:3] op_sel_hi:[1,0]
	v_pk_fma_f32 v[72:73], v[52:53], v[72:73], v[88:89]
	v_pk_fma_f32 v[14:15], v[54:55], v[14:15], v[104:105]
	v_and_b32_sdwa v2, v73, v202 dst_sel:DWORD dst_unused:UNUSED_PAD src0_sel:WORD_1 src1_sel:DWORD
	v_and_b32_sdwa v74, v72, v202 dst_sel:DWORD dst_unused:UNUSED_PAD src0_sel:WORD_1 src1_sel:DWORD
	v_add3_u32 v72, v72, v74, s5
	v_add3_u32 v2, v73, v2, s5
	v_and_b32_sdwa v73, v15, v202 dst_sel:DWORD dst_unused:UNUSED_PAD src0_sel:WORD_1 src1_sel:DWORD
	v_and_b32_sdwa v74, v14, v202 dst_sel:DWORD dst_unused:UNUSED_PAD src0_sel:WORD_1 src1_sel:DWORD
	v_add3_u32 v15, v15, v73, s5
	v_add3_u32 v14, v14, v74, s5
	v_and_b32_e32 v15, 0xffff0000, v15
	v_and_b32_e32 v14, 0xffff0000, v14
	v_readlane_b32 s2, v250, 47
	v_lshl_add_u64 v[12:13], v[28:29], 0, s[10:11]
	v_or_b32_sdwa v15, v15, v2 dst_sel:DWORD dst_unused:UNUSED_PAD src0_sel:DWORD src1_sel:WORD_1
	v_or_b32_sdwa v14, v14, v72 dst_sel:DWORD dst_unused:UNUSED_PAD src0_sel:DWORD src1_sel:WORD_1
	s_add_i32 s6, s6, s2
	s_andn2_b64 vcc, exec, s[8:9]
	v_mov_b64_e32 v[72:73], v[44:45]
	v_mov_b64_e32 v[76:77], v[46:47]
	v_mov_b64_e32 v[78:79], v[48:49]
	v_mov_b64_e32 v[82:83], v[50:51]
	v_mov_b64_e32 v[74:75], v[36:37]
	v_mov_b64_e32 v[80:81], v[38:39]
	v_mov_b64_e32 v[84:85], v[40:41]
	v_mov_b64_e32 v[86:87], v[42:43]
	v_mov_b64_e32 v[88:89], v[64:65]
	v_mov_b64_e32 v[92:93], v[66:67]
	v_mov_b64_e32 v[98:99], v[68:69]
	v_mov_b64_e32 v[102:103], v[70:71]
	v_mov_b64_e32 v[90:91], v[56:57]
	v_mov_b64_e32 v[94:95], v[58:59]
	v_mov_b64_e32 v[96:97], v[60:61]
	v_mov_b64_e32 v[100:101], v[62:63]
	s_mov_b32 s7, s50
	global_store_dwordx2 v[12:13], v[14:15], off sc0 sc1
	s_cbranch_vccz .LBB0_1160

.LBB0_1158:
	s_or_b64 exec, exec, s[10:11]
	v_lshl_add_u32 v2, v1, 2, s28
	v_lshlrev_b32_e32 v122, 16, v72
	s_waitcnt lgkmcnt(0)
	v_and_b32_e32 v120, 0xffff0000, v72
	s_barrier
	ds_read_b32 v72, v2
	v_lshlrev_b32_e32 v123, 16, v73
	v_and_b32_e32 v121, 0xffff0000, v73
	s_mov_b32 s2, 0x800000
	v_lshlrev_b32_e32 v140, 16, v84
	s_waitcnt lgkmcnt(0)
	ds_bpermute_b32 v73, v149, v72
	v_and_b32_e32 v138, 0xffff0000, v84
	v_lshlrev_b32_e32 v134, 16, v74
	v_and_b32_e32 v84, 0xffff0000, v74
	v_and_b32_e32 v143, 0xffff0000, v87
	s_waitcnt lgkmcnt(0)
	v_add_f32_e32 v72, v72, v73
	ds_bpermute_b32 v73, v150, v72
	v_and_b32_e32 v142, 0xffff0000, v86
	v_lshlrev_b32_e32 v141, 16, v85
	v_and_b32_e32 v139, 0xffff0000, v85
	v_lshlrev_b32_e32 v135, 16, v75
	s_waitcnt lgkmcnt(0)
	v_add_f32_e32 v72, v72, v73
	ds_bpermute_b32 v73, v151, v72
	v_and_b32_e32 v85, 0xffff0000, v75
	v_lshlrev_b32_e32 v130, 16, v78
	v_and_b32_e32 v128, 0xffff0000, v78
	v_lshlrev_b32_e32 v131, 16, v79
	s_waitcnt lgkmcnt(0)
	v_add_f32_e32 v72, v72, v73
	v_and_b32_e32 v129, 0xffff0000, v79
	v_readlane_b32 s13, v72, 0
	v_readlane_b32 s14, v72, 1
	v_readlane_b32 s15, v72, 2
	v_readlane_b32 s16, v72, 3
	v_readlane_b32 s12, v72, 4
	v_readlane_b32 s11, v72, 5
	v_readlane_b32 s10, v72, 6
	v_readlane_b32 s7, v72, 7
	v_fma_f32 v72, s13, v206, v203
	v_cmp_gt_f32_e32 vcc, s2, v72
	v_mul_f32_e32 v73, 0x4b800000, v72
	v_fma_f32 v78, s15, v206, v203
	v_cndmask_b32_e32 v72, v72, v73, vcc
	v_rsq_f32_e32 v72, v72
	v_lshlrev_b32_e32 v126, 16, v76
	v_and_b32_e32 v124, 0xffff0000, v76
	v_mul_f32_e32 v79, 0x4b800000, v78
	v_mul_f32_e32 v73, 0x45800000, v72
	v_cndmask_b32_e32 v74, v72, v73, vcc
	v_pk_mul_f32 v[72:73], v[118:119], v[74:75] op_sel_hi:[1,0]
	v_mov_b32_e32 v119, v14
	v_pk_mul_f32 v[74:75], v[110:111], v[74:75] op_sel_hi:[1,0]
	v_mov_b32_e32 v14, v13
	v_mov_b32_e32 v118, v12
	v_pk_fma_f32 v[12:13], v[14:15], v[74:75], v[142:143]
	v_fma_f32 v74, s14, v206, v203
	v_cmp_gt_f32_e32 vcc, s2, v74
	v_mul_f32_e32 v75, 0x4b800000, v74
	v_lshlrev_b32_e32 v144, 16, v86
	v_cndmask_b32_e32 v74, v74, v75, vcc
	v_rsq_f32_e32 v74, v74
	v_lshlrev_b32_e32 v86, 16, v82
	v_and_b32_e32 v132, 0xffff0000, v82
	v_lshlrev_b32_e32 v145, 16, v87
	v_mul_f32_e32 v75, 0x45800000, v74
	v_cndmask_b32_e32 v76, v74, v75, vcc
	v_cmp_gt_f32_e32 vcc, s2, v78
	v_lshlrev_b32_e32 v137, 16, v81
	v_lshlrev_b32_e32 v136, 16, v80
	v_cndmask_b32_e32 v78, v78, v79, vcc
	v_rsq_f32_e32 v78, v78
	v_and_b32_e32 v81, 0xffff0000, v81
	v_and_b32_e32 v80, 0xffff0000, v80
	v_lshlrev_b32_e32 v87, 16, v83
	v_mul_f32_e32 v79, 0x45800000, v78
	v_cndmask_b32_e32 v82, v78, v79, vcc
	v_and_b32_e32 v133, 0xffff0000, v83
	v_pk_mul_f32 v[78:79], v[114:115], v[82:83] op_sel_hi:[1,0]
	v_pk_mul_f32 v[82:83], v[104:105], v[82:83] op_sel_hi:[1,0]
	v_pk_fma_f32 v[72:73], v[118:119], v[72:73], v[144:145]
	v_pk_fma_f32 v[80:81], v[14:15], v[82:83], v[80:81]
	v_fma_f32 v82, s16, v206, v203
	v_cmp_gt_f32_e32 vcc, s2, v82
	v_mul_f32_e32 v83, 0x4b800000, v82
	v_lshlrev_b32_e32 v127, 16, v77
	v_cndmask_b32_e32 v82, v82, v83, vcc
	v_rsq_f32_e32 v82, v82
	v_and_b32_e32 v125, 0xffff0000, v77
	v_pk_mul_f32 v[74:75], v[116:117], v[76:77] op_sel_hi:[1,0]
	v_pk_mul_f32 v[76:77], v[106:107], v[76:77] op_sel_hi:[1,0]
	v_mul_f32_e32 v83, 0x45800000, v82
	v_cndmask_b32_e32 v104, v82, v83, vcc
	v_pk_mul_f32 v[100:101], v[100:101], v[104:105] op_sel_hi:[1,0]
	v_pk_mul_f32 v[82:83], v[112:113], v[104:105] op_sel_hi:[1,0]
	v_pk_fma_f32 v[84:85], v[14:15], v[100:101], v[84:85]
	v_fma_f32 v100, s12, v206, v203
	v_cmp_gt_f32_e32 vcc, s2, v100
	v_mul_f32_e32 v101, 0x4b800000, v100
	v_pk_fma_f32 v[74:75], v[118:119], v[74:75], v[140:141]
	v_cndmask_b32_e32 v100, v100, v101, vcc
	v_rsq_f32_e32 v100, v100
	v_pk_fma_f32 v[76:77], v[14:15], v[76:77], v[138:139]
	v_pk_fma_f32 v[78:79], v[118:119], v[78:79], v[136:137]
	v_pk_fma_f32 v[82:83], v[118:119], v[82:83], v[134:135]
	v_mul_f32_e32 v101, 0x45800000, v100
	v_cndmask_b32_e32 v100, v100, v101, vcc
	v_pk_mul_f32 v[104:105], v[108:109], v[100:101] op_sel_hi:[1,0]
	v_pk_mul_f32 v[96:97], v[96:97], v[100:101] op_sel_hi:[1,0]
	v_fma_f32 v100, s11, v206, v203
	v_cmp_gt_f32_e32 vcc, s2, v100
	v_mul_f32_e32 v101, 0x4b800000, v100
	v_pk_fma_f32 v[86:87], v[118:119], v[104:105], v[86:87]
	v_cndmask_b32_e32 v100, v100, v101, vcc
	v_rsq_f32_e32 v100, v100
	v_pk_fma_f32 v[96:97], v[14:15], v[96:97], v[132:133]
	v_mul_f32_e32 v101, 0x45800000, v100
	v_cndmask_b32_e32 v104, v100, v101, vcc
	v_pk_mul_f32 v[100:101], v[102:103], v[104:105] op_sel_hi:[1,0]
	v_fma_f32 v102, s10, v206, v203
	v_cmp_gt_f32_e32 vcc, s2, v102
	v_mul_f32_e32 v103, 0x4b800000, v102
	v_pk_mul_f32 v[94:95], v[94:95], v[104:105] op_sel_hi:[1,0]
	v_cndmask_b32_e32 v102, v102, v103, vcc
	v_rsq_f32_e32 v102, v102
	v_and_b32_sdwa v105, v12, v202 dst_sel:DWORD dst_unused:UNUSED_PAD src0_sel:WORD_1 src1_sel:DWORD
	v_add3_u32 v105, v12, v105, s5
	v_and_b32_e32 v105, 0xffff0000, v105
	v_mul_f32_e32 v103, 0x45800000, v102
	v_cndmask_b32_e32 v102, v102, v103, vcc
	v_pk_mul_f32 v[98:99], v[98:99], v[102:103] op_sel_hi:[1,0]
	v_pk_mul_f32 v[90:91], v[90:91], v[102:103] op_sel_hi:[1,0]
	v_fma_f32 v102, s7, v206, v203
	v_cmp_gt_f32_e32 vcc, s2, v102
	v_mul_f32_e32 v103, 0x4b800000, v102
	s_ashr_i32 s7, s6, 31
	v_cndmask_b32_e32 v102, v102, v103, vcc
	v_rsq_f32_e32 v102, v102
	s_lshl_b64 s[26:27], s[6:7], 12
	v_pk_fma_f32 v[94:95], v[14:15], v[94:95], v[128:129]
	v_pk_fma_f32 v[90:91], v[14:15], v[90:91], v[124:125]
	v_mul_f32_e32 v103, 0x45800000, v102
	v_cndmask_b32_e32 v102, v102, v103, vcc
	v_pk_mul_f32 v[92:93], v[92:93], v[102:103] op_sel_hi:[1,0]
	v_pk_mul_f32 v[88:89], v[88:89], v[102:103] op_sel_hi:[1,0]
	v_and_b32_sdwa v103, v72, v202 dst_sel:DWORD dst_unused:UNUSED_PAD src0_sel:WORD_1 src1_sel:DWORD
	v_add3_u32 v104, v72, v103, s5
	v_and_b32_sdwa v103, v13, v202 dst_sel:DWORD dst_unused:UNUSED_PAD src0_sel:WORD_1 src1_sel:DWORD
	v_and_b32_sdwa v102, v73, v202 dst_sel:DWORD dst_unused:UNUSED_PAD src0_sel:WORD_1 src1_sel:DWORD
	v_add3_u32 v103, v13, v103, s5
	v_add3_u32 v102, v73, v102, s5
	v_and_b32_e32 v103, 0xffff0000, v103
	v_pk_fma_f32 v[14:15], v[14:15], v[88:89], v[120:121]
	v_lshl_add_u64 v[88:89], v[24:25], 0, s[26:27]
	v_or_b32_sdwa v103, v103, v102 dst_sel:DWORD dst_unused:UNUSED_PAD src0_sel:DWORD src1_sel:WORD_1
	v_or_b32_sdwa v102, v105, v104 dst_sel:DWORD dst_unused:UNUSED_PAD src0_sel:DWORD src1_sel:WORD_1
	global_store_dwordx2 v[88:89], v[102:103], off sc0 sc1
	v_and_b32_sdwa v103, v74, v202 dst_sel:DWORD dst_unused:UNUSED_PAD src0_sel:WORD_1 src1_sel:DWORD
	s_add_i32 s10, s6, 1
	v_add3_u32 v104, v74, v103, s5
	v_and_b32_sdwa v103, v77, v202 dst_sel:DWORD dst_unused:UNUSED_PAD src0_sel:WORD_1 src1_sel:DWORD
	v_and_b32_sdwa v105, v76, v202 dst_sel:DWORD dst_unused:UNUSED_PAD src0_sel:WORD_1 src1_sel:DWORD
	s_ashr_i32 s11, s10, 31
	v_and_b32_sdwa v102, v75, v202 dst_sel:DWORD dst_unused:UNUSED_PAD src0_sel:WORD_1 src1_sel:DWORD
	v_add3_u32 v103, v77, v103, s5
	v_add3_u32 v105, v76, v105, s5
	s_lshl_b64 s[24:25], s[10:11], 12
	v_add3_u32 v102, v75, v102, s5
	v_and_b32_e32 v103, 0xffff0000, v103
	v_and_b32_e32 v105, 0xffff0000, v105
	v_lshl_add_u64 v[88:89], v[24:25], 0, s[24:25]
	v_or_b32_sdwa v103, v103, v102 dst_sel:DWORD dst_unused:UNUSED_PAD src0_sel:DWORD src1_sel:WORD_1
	v_or_b32_sdwa v102, v105, v104 dst_sel:DWORD dst_unused:UNUSED_PAD src0_sel:DWORD src1_sel:WORD_1
	global_store_dwordx2 v[88:89], v[102:103], off sc0 sc1
	v_and_b32_sdwa v103, v78, v202 dst_sel:DWORD dst_unused:UNUSED_PAD src0_sel:WORD_1 src1_sel:DWORD
	s_add_i32 s10, s6, 2
	v_add3_u32 v104, v78, v103, s5
	v_and_b32_sdwa v103, v81, v202 dst_sel:DWORD dst_unused:UNUSED_PAD src0_sel:WORD_1 src1_sel:DWORD
	v_and_b32_sdwa v105, v80, v202 dst_sel:DWORD dst_unused:UNUSED_PAD src0_sel:WORD_1 src1_sel:DWORD
	s_ashr_i32 s11, s10, 31
	v_and_b32_sdwa v102, v79, v202 dst_sel:DWORD dst_unused:UNUSED_PAD src0_sel:WORD_1 src1_sel:DWORD
	v_add3_u32 v103, v81, v103, s5
	v_add3_u32 v105, v80, v105, s5
	s_lshl_b64 s[20:21], s[10:11], 12
	v_add3_u32 v102, v79, v102, s5
	v_and_b32_e32 v103, 0xffff0000, v103
	v_and_b32_e32 v105, 0xffff0000, v105
	v_lshl_add_u64 v[88:89], v[24:25], 0, s[20:21]
	v_or_b32_sdwa v103, v103, v102 dst_sel:DWORD dst_unused:UNUSED_PAD src0_sel:DWORD src1_sel:WORD_1
	v_or_b32_sdwa v102, v105, v104 dst_sel:DWORD dst_unused:UNUSED_PAD src0_sel:DWORD src1_sel:WORD_1
	global_store_dwordx2 v[88:89], v[102:103], off sc0 sc1
	v_and_b32_sdwa v103, v82, v202 dst_sel:DWORD dst_unused:UNUSED_PAD src0_sel:WORD_1 src1_sel:DWORD
	s_add_i32 s10, s6, 3
	v_add3_u32 v104, v82, v103, s5
	v_and_b32_sdwa v103, v85, v202 dst_sel:DWORD dst_unused:UNUSED_PAD src0_sel:WORD_1 src1_sel:DWORD
	v_and_b32_sdwa v105, v84, v202 dst_sel:DWORD dst_unused:UNUSED_PAD src0_sel:WORD_1 src1_sel:DWORD
	s_ashr_i32 s11, s10, 31
	v_and_b32_sdwa v102, v83, v202 dst_sel:DWORD dst_unused:UNUSED_PAD src0_sel:WORD_1 src1_sel:DWORD
	v_add3_u32 v103, v85, v103, s5
	v_add3_u32 v105, v84, v105, s5
	s_lshl_b64 s[18:19], s[10:11], 12
	v_add3_u32 v102, v83, v102, s5
	v_and_b32_e32 v103, 0xffff0000, v103
	v_and_b32_e32 v105, 0xffff0000, v105
	v_lshl_add_u64 v[88:89], v[24:25], 0, s[18:19]
	v_or_b32_sdwa v103, v103, v102 dst_sel:DWORD dst_unused:UNUSED_PAD src0_sel:DWORD src1_sel:WORD_1
	v_or_b32_sdwa v102, v105, v104 dst_sel:DWORD dst_unused:UNUSED_PAD src0_sel:DWORD src1_sel:WORD_1
	global_store_dwordx2 v[88:89], v[102:103], off sc0 sc1
	v_and_b32_sdwa v103, v86, v202 dst_sel:DWORD dst_unused:UNUSED_PAD src0_sel:WORD_1 src1_sel:DWORD
	s_add_i32 s10, s6, 4
	v_add3_u32 v104, v86, v103, s5
	v_and_b32_sdwa v103, v97, v202 dst_sel:DWORD dst_unused:UNUSED_PAD src0_sel:WORD_1 src1_sel:DWORD
	v_and_b32_sdwa v105, v96, v202 dst_sel:DWORD dst_unused:UNUSED_PAD src0_sel:WORD_1 src1_sel:DWORD
	s_ashr_i32 s11, s10, 31
	v_and_b32_sdwa v102, v87, v202 dst_sel:DWORD dst_unused:UNUSED_PAD src0_sel:WORD_1 src1_sel:DWORD
	v_add3_u32 v103, v97, v103, s5
	v_add3_u32 v105, v96, v105, s5
	s_lshl_b64 s[16:17], s[10:11], 12
	v_add3_u32 v102, v87, v102, s5
	v_and_b32_e32 v103, 0xffff0000, v103
	v_and_b32_e32 v105, 0xffff0000, v105
	v_pk_fma_f32 v[100:101], v[118:119], v[100:101], v[130:131]
	v_lshl_add_u64 v[88:89], v[24:25], 0, s[16:17]
	v_or_b32_sdwa v103, v103, v102 dst_sel:DWORD dst_unused:UNUSED_PAD src0_sel:DWORD src1_sel:WORD_1
	v_or_b32_sdwa v102, v105, v104 dst_sel:DWORD dst_unused:UNUSED_PAD src0_sel:DWORD src1_sel:WORD_1
	global_store_dwordx2 v[88:89], v[102:103], off sc0 sc1
	v_and_b32_sdwa v103, v100, v202 dst_sel:DWORD dst_unused:UNUSED_PAD src0_sel:WORD_1 src1_sel:DWORD
	s_add_i32 s10, s6, 5
	v_add3_u32 v104, v100, v103, s5
	v_and_b32_sdwa v103, v95, v202 dst_sel:DWORD dst_unused:UNUSED_PAD src0_sel:WORD_1 src1_sel:DWORD
	v_and_b32_sdwa v105, v94, v202 dst_sel:DWORD dst_unused:UNUSED_PAD src0_sel:WORD_1 src1_sel:DWORD
	s_ashr_i32 s11, s10, 31
	v_and_b32_sdwa v102, v101, v202 dst_sel:DWORD dst_unused:UNUSED_PAD src0_sel:WORD_1 src1_sel:DWORD
	v_add3_u32 v103, v95, v103, s5
	v_add3_u32 v105, v94, v105, s5
	s_lshl_b64 s[14:15], s[10:11], 12
	v_add3_u32 v102, v101, v102, s5
	v_and_b32_e32 v103, 0xffff0000, v103
	v_and_b32_e32 v105, 0xffff0000, v105
	v_pk_fma_f32 v[98:99], v[118:119], v[98:99], v[126:127]
	v_lshl_add_u64 v[88:89], v[24:25], 0, s[14:15]
	v_or_b32_sdwa v103, v103, v102 dst_sel:DWORD dst_unused:UNUSED_PAD src0_sel:DWORD src1_sel:WORD_1
	v_or_b32_sdwa v102, v105, v104 dst_sel:DWORD dst_unused:UNUSED_PAD src0_sel:DWORD src1_sel:WORD_1
	global_store_dwordx2 v[88:89], v[102:103], off sc0 sc1
	v_and_b32_sdwa v103, v98, v202 dst_sel:DWORD dst_unused:UNUSED_PAD src0_sel:WORD_1 src1_sel:DWORD
	s_add_i32 s10, s6, 6
	v_add3_u32 v104, v98, v103, s5
	v_and_b32_sdwa v103, v91, v202 dst_sel:DWORD dst_unused:UNUSED_PAD src0_sel:WORD_1 src1_sel:DWORD
	v_and_b32_sdwa v105, v90, v202 dst_sel:DWORD dst_unused:UNUSED_PAD src0_sel:WORD_1 src1_sel:DWORD
	s_ashr_i32 s11, s10, 31
	v_and_b32_sdwa v102, v99, v202 dst_sel:DWORD dst_unused:UNUSED_PAD src0_sel:WORD_1 src1_sel:DWORD
	v_add3_u32 v103, v91, v103, s5
	v_add3_u32 v105, v90, v105, s5
	s_lshl_b64 s[12:13], s[10:11], 12
	v_add3_u32 v102, v99, v102, s5
	v_and_b32_e32 v103, 0xffff0000, v103
	v_and_b32_e32 v105, 0xffff0000, v105
	v_pk_fma_f32 v[92:93], v[118:119], v[92:93], v[122:123]
	v_lshl_add_u64 v[88:89], v[24:25], 0, s[12:13]
	v_or_b32_sdwa v103, v103, v102 dst_sel:DWORD dst_unused:UNUSED_PAD src0_sel:DWORD src1_sel:WORD_1
	v_or_b32_sdwa v102, v105, v104 dst_sel:DWORD dst_unused:UNUSED_PAD src0_sel:DWORD src1_sel:WORD_1
	global_store_dwordx2 v[88:89], v[102:103], off sc0 sc1
	v_and_b32_sdwa v103, v92, v202 dst_sel:DWORD dst_unused:UNUSED_PAD src0_sel:WORD_1 src1_sel:DWORD
	s_add_i32 s10, s6, 7
	v_add3_u32 v104, v92, v103, s5
	v_and_b32_sdwa v103, v15, v202 dst_sel:DWORD dst_unused:UNUSED_PAD src0_sel:WORD_1 src1_sel:DWORD
	v_and_b32_sdwa v105, v14, v202 dst_sel:DWORD dst_unused:UNUSED_PAD src0_sel:WORD_1 src1_sel:DWORD
	s_ashr_i32 s11, s10, 31
	v_and_b32_sdwa v102, v93, v202 dst_sel:DWORD dst_unused:UNUSED_PAD src0_sel:WORD_1 src1_sel:DWORD
	v_add3_u32 v103, v15, v103, s5
	v_add3_u32 v105, v14, v105, s5
	s_lshl_b64 s[10:11], s[10:11], 12
	v_add3_u32 v102, v93, v102, s5
	v_and_b32_e32 v103, 0xffff0000, v103
	v_and_b32_e32 v105, 0xffff0000, v105
	v_lshl_add_u64 v[88:89], v[24:25], 0, s[10:11]
	v_or_b32_sdwa v103, v103, v102 dst_sel:DWORD dst_unused:UNUSED_PAD src0_sel:DWORD src1_sel:WORD_1
	v_or_b32_sdwa v102, v105, v104 dst_sel:DWORD dst_unused:UNUSED_PAD src0_sel:DWORD src1_sel:WORD_1
	global_store_dwordx2 v[88:89], v[102:103], off sc0 sc1
	v_pk_mul_f32 v[88:89], v[72:73], v[72:73]
	v_pk_mul_f32 v[102:103], v[12:13], v[12:13]
	s_nop 0
	v_add_f32_e32 v88, v88, v102
	v_add_f32_e32 v88, v89, v88
	v_add_f32_e32 v104, v103, v88
	v_pk_mul_f32 v[88:89], v[74:75], v[74:75]
	v_pk_mul_f32 v[102:103], v[76:77], v[76:77]
	s_nop 0
	v_add_f32_e32 v88, v88, v102
	v_add_f32_e32 v88, v89, v88
	v_add_f32_e32 v105, v103, v88
	v_pk_mul_f32 v[88:89], v[78:79], v[78:79]
	v_pk_mul_f32 v[102:103], v[80:81], v[80:81]
	s_nop 0
	v_add_f32_e32 v88, v88, v102
	v_add_f32_e32 v88, v89, v88
	v_add_f32_e32 v106, v103, v88
	v_pk_mul_f32 v[88:89], v[82:83], v[82:83]
	v_pk_mul_f32 v[102:103], v[84:85], v[84:85]
	s_nop 0
	v_add_f32_e32 v88, v88, v102
	v_add_f32_e32 v88, v89, v88
	v_add_f32_e32 v107, v103, v88
	v_pk_mul_f32 v[88:89], v[86:87], v[86:87]
	v_pk_mul_f32 v[102:103], v[96:97], v[96:97]
	s_nop 0
	v_add_f32_e32 v88, v88, v102
	v_add_f32_e32 v88, v89, v88
	v_add_f32_e32 v108, v103, v88
	v_pk_mul_f32 v[88:89], v[100:101], v[100:101]
	v_pk_mul_f32 v[102:103], v[94:95], v[94:95]
	s_nop 0
	v_add_f32_e32 v88, v88, v102
	v_add_f32_e32 v88, v89, v88
	v_add_f32_e32 v109, v103, v88
	v_pk_mul_f32 v[88:89], v[98:99], v[98:99]
	v_pk_mul_f32 v[102:103], v[90:91], v[90:91]
	s_nop 0
	v_add_f32_e32 v88, v88, v102
	v_add_f32_e32 v88, v89, v88
	v_add_f32_e32 v110, v103, v88
	v_pk_mul_f32 v[88:89], v[92:93], v[92:93]
	v_pk_mul_f32 v[102:103], v[14:15], v[14:15]
	s_nop 0
	v_add_f32_e32 v88, v88, v102
	v_add_f32_e32 v88, v89, v88
	v_cndmask_b32_e64 v102, v104, v108, s[40:41]
	v_add_f32_e32 v88, v103, v88
	ds_bpermute_b32 v102, v146, v102
	v_cndmask_b32_e64 v103, v105, v109, s[40:41]
	v_cndmask_b32_e64 v89, v108, v104, s[40:41]
	ds_bpermute_b32 v103, v146, v103
	v_cndmask_b32_e64 v104, v106, v110, s[40:41]
	ds_bpermute_b32 v104, v146, v104
	s_waitcnt lgkmcnt(2)
	v_add_f32_e32 v89, v89, v102
	v_cndmask_b32_e64 v102, v109, v105, s[40:41]
	s_waitcnt lgkmcnt(1)
	v_add_f32_e32 v102, v102, v103
	v_cndmask_b32_e64 v103, v110, v106, s[40:41]
	s_waitcnt lgkmcnt(0)
	v_add_f32_e32 v103, v103, v104
	v_cndmask_b32_e64 v104, v88, v107, s[40:41]
	v_cndmask_b32_e64 v88, v107, v88, s[40:41]
	ds_bpermute_b32 v88, v146, v88
	s_waitcnt lgkmcnt(0)
	v_add_f32_e32 v88, v104, v88
	v_cndmask_b32_e64 v104, v103, v89, s[42:43]
	v_cndmask_b32_e64 v89, v89, v103, s[42:43]
	v_cndmask_b32_e64 v103, v88, v102, s[42:43]
	v_cndmask_b32_e64 v88, v102, v88, s[42:43]
	ds_bpermute_b32 v89, v147, v89
	ds_bpermute_b32 v88, v147, v88
	s_waitcnt lgkmcnt(1)
	v_add_f32_e32 v89, v104, v89
	s_waitcnt lgkmcnt(0)
	v_add_f32_e32 v88, v103, v88
	v_cndmask_b32_e64 v102, v88, v89, s[44:45]
	v_cndmask_b32_e64 v88, v89, v88, s[44:45]
	ds_bpermute_b32 v88, v148, v88
	s_waitcnt lgkmcnt(0)
	v_add_f32_e32 v88, v102, v88
	ds_bpermute_b32 v89, v149, v88
	s_waitcnt lgkmcnt(0)
	v_add_f32_e32 v88, v88, v89
	ds_bpermute_b32 v89, v150, v88
	s_waitcnt lgkmcnt(0)
	v_add_f32_e32 v88, v88, v89
	ds_bpermute_b32 v89, v151, v88
	s_and_saveexec_b64 s[34:35], s[46:47]
	s_cbranch_execz .LBB0_1149
	v_readlane_b32 s2, v250, 55
	s_add_i32 s28, s28, s2
	v_lshl_add_u32 v102, v1, 2, s28
	s_waitcnt lgkmcnt(0)
	v_add_f32_e32 v88, v88, v89
	ds_write_b32 v102, v88 offset:256
	s_branch .LBB0_1149

.LBB0_1355:
	s_or_b64 exec, exec, s[10:11]
	s_waitcnt lgkmcnt(0)
	s_barrier
	ds_read_b32 v2, v2 offset:256
	v_mov_b32_e32 v91, v6
	s_waitcnt lgkmcnt(0)
	ds_bpermute_b32 v90, v141, v2
	s_waitcnt lgkmcnt(0)
	v_add_f32_e32 v2, v2, v90
	ds_bpermute_b32 v90, v142, v2
	s_waitcnt lgkmcnt(0)
	v_add_f32_e32 v2, v2, v90
	ds_bpermute_b32 v90, v143, v2
	s_waitcnt lgkmcnt(0)
	v_add_f32_e32 v2, v2, v90
	s_nop 0
	v_readlane_b32 s1, v2, 0
	v_readlane_b32 s16, v2, 1
	v_readlane_b32 s15, v2, 2
	v_readlane_b32 s14, v2, 3
	v_readlane_b32 s13, v2, 4
	v_readlane_b32 s12, v2, 5
	v_readlane_b32 s11, v2, 6
	v_readlane_b32 s10, v2, 7
	v_fma_f32 v2, s1, v206, v203
	v_cmp_gt_f32_e32 vcc, s2, v2
	v_mul_f32_e32 v90, 0x4b800000, v2
	s_ashr_i32 s1, s0, 31
	v_cndmask_b32_e32 v2, v2, v90, vcc
	v_rsq_f32_e32 v2, v2
	s_lshl_b64 s[18:19], s[0:1], 12
	v_lshl_add_u64 v[102:103], v[28:29], 0, s[18:19]
	v_mul_f32_e32 v90, 0x45800000, v2
	v_cndmask_b32_e32 v2, v2, v90, vcc
	v_pk_mul_f32 v[100:101], v[112:113], v[2:3] op_sel_hi:[1,0]
	v_mov_b32_e32 v90, v4
	v_pk_fma_f32 v[104:105], v[54:55], v[100:101], v[90:91]
	v_pk_mul_f32 v[106:107], v[110:111], v[2:3] op_sel_hi:[1,0]
	v_mov_b32_e32 v100, v5
	v_mov_b32_e32 v101, v7
	v_pk_fma_f32 v[106:107], v[72:73], v[106:107], v[100:101]
	v_and_b32_sdwa v2, v105, v202 dst_sel:DWORD dst_unused:UNUSED_PAD src0_sel:WORD_1 src1_sel:DWORD
	v_and_b32_sdwa v108, v104, v202 dst_sel:DWORD dst_unused:UNUSED_PAD src0_sel:WORD_1 src1_sel:DWORD
	v_add3_u32 v104, v104, v108, s5
	v_add3_u32 v2, v105, v2, s5
	v_and_b32_sdwa v105, v107, v202 dst_sel:DWORD dst_unused:UNUSED_PAD src0_sel:WORD_1 src1_sel:DWORD
	v_and_b32_sdwa v108, v106, v202 dst_sel:DWORD dst_unused:UNUSED_PAD src0_sel:WORD_1 src1_sel:DWORD
	v_add3_u32 v105, v107, v105, s5
	v_add3_u32 v106, v106, v108, s5
	v_and_b32_e32 v105, 0xffff0000, v105
	v_and_b32_e32 v106, 0xffff0000, v106
	v_or_b32_sdwa v105, v105, v2 dst_sel:DWORD dst_unused:UNUSED_PAD src0_sel:DWORD src1_sel:WORD_1
	v_or_b32_sdwa v104, v106, v104 dst_sel:DWORD dst_unused:UNUSED_PAD src0_sel:DWORD src1_sel:WORD_1
	v_fma_f32 v2, s16, v206, v203
	global_store_dwordx2 v[102:103], v[104:105], off sc0 sc1
	v_cmp_gt_f32_e32 vcc, s2, v2
	v_mul_f32_e32 v102, 0x4b800000, v2
	s_add_i32 s16, s0, 1
	v_cndmask_b32_e32 v2, v2, v102, vcc
	v_rsq_f32_e32 v2, v2
	s_ashr_i32 s17, s16, 31
	s_lshl_b64 s[16:17], s[16:17], 12
	v_mul_f32_e32 v102, 0x45800000, v2
	v_cndmask_b32_e32 v2, v2, v102, vcc
	v_pk_mul_f32 v[98:99], v[98:99], v[2:3] op_sel_hi:[1,0]
	v_pk_mul_f32 v[96:97], v[96:97], v[2:3] op_sel_hi:[1,0]
	v_pk_fma_f32 v[98:99], v[54:55], v[98:99], v[90:91]
	v_pk_fma_f32 v[96:97], v[72:73], v[96:97], v[100:101]
	v_and_b32_sdwa v2, v99, v202 dst_sel:DWORD dst_unused:UNUSED_PAD src0_sel:WORD_1 src1_sel:DWORD
	v_and_b32_sdwa v104, v98, v202 dst_sel:DWORD dst_unused:UNUSED_PAD src0_sel:WORD_1 src1_sel:DWORD
	v_add3_u32 v98, v98, v104, s5
	v_add3_u32 v2, v99, v2, s5
	v_and_b32_sdwa v99, v97, v202 dst_sel:DWORD dst_unused:UNUSED_PAD src0_sel:WORD_1 src1_sel:DWORD
	v_and_b32_sdwa v104, v96, v202 dst_sel:DWORD dst_unused:UNUSED_PAD src0_sel:WORD_1 src1_sel:DWORD
	v_add3_u32 v97, v97, v99, s5
	v_add3_u32 v96, v96, v104, s5
	v_and_b32_e32 v97, 0xffff0000, v97
	v_and_b32_e32 v96, 0xffff0000, v96
	v_lshl_add_u64 v[102:103], v[28:29], 0, s[16:17]
	v_or_b32_sdwa v97, v97, v2 dst_sel:DWORD dst_unused:UNUSED_PAD src0_sel:DWORD src1_sel:WORD_1
	v_or_b32_sdwa v96, v96, v98 dst_sel:DWORD dst_unused:UNUSED_PAD src0_sel:DWORD src1_sel:WORD_1
	v_fma_f32 v2, s15, v206, v203
	global_store_dwordx2 v[102:103], v[96:97], off sc0 sc1
	v_cmp_gt_f32_e32 vcc, s2, v2
	v_mul_f32_e32 v96, 0x4b800000, v2
	s_add_i32 s16, s0, 2
	v_cndmask_b32_e32 v2, v2, v96, vcc
	v_rsq_f32_e32 v2, v2
	s_ashr_i32 s17, s16, 31
	s_lshl_b64 s[16:17], s[16:17], 12
	v_mul_f32_e32 v96, 0x45800000, v2
	v_cndmask_b32_e32 v2, v2, v96, vcc
	v_pk_mul_f32 v[94:95], v[94:95], v[2:3] op_sel_hi:[1,0]
	v_pk_mul_f32 v[92:93], v[92:93], v[2:3] op_sel_hi:[1,0]
	v_pk_fma_f32 v[94:95], v[54:55], v[94:95], v[90:91]
	v_pk_fma_f32 v[92:93], v[72:73], v[92:93], v[100:101]
	v_and_b32_sdwa v2, v95, v202 dst_sel:DWORD dst_unused:UNUSED_PAD src0_sel:WORD_1 src1_sel:DWORD
	v_and_b32_sdwa v98, v94, v202 dst_sel:DWORD dst_unused:UNUSED_PAD src0_sel:WORD_1 src1_sel:DWORD
	v_add3_u32 v94, v94, v98, s5
	v_add3_u32 v2, v95, v2, s5
	v_and_b32_sdwa v95, v93, v202 dst_sel:DWORD dst_unused:UNUSED_PAD src0_sel:WORD_1 src1_sel:DWORD
	v_and_b32_sdwa v98, v92, v202 dst_sel:DWORD dst_unused:UNUSED_PAD src0_sel:WORD_1 src1_sel:DWORD
	v_add3_u32 v93, v93, v95, s5
	v_add3_u32 v92, v92, v98, s5
	v_and_b32_e32 v93, 0xffff0000, v93
	v_and_b32_e32 v92, 0xffff0000, v92
	v_lshl_add_u64 v[96:97], v[28:29], 0, s[16:17]
	v_or_b32_sdwa v93, v93, v2 dst_sel:DWORD dst_unused:UNUSED_PAD src0_sel:DWORD src1_sel:WORD_1
	v_or_b32_sdwa v92, v92, v94 dst_sel:DWORD dst_unused:UNUSED_PAD src0_sel:DWORD src1_sel:WORD_1
	v_fma_f32 v2, s14, v206, v203
	global_store_dwordx2 v[96:97], v[92:93], off sc0 sc1
	v_cmp_gt_f32_e32 vcc, s2, v2
	v_mul_f32_e32 v92, 0x4b800000, v2
	s_add_i32 s14, s0, 3
	v_cndmask_b32_e32 v2, v2, v92, vcc
	v_rsq_f32_e32 v2, v2
	s_ashr_i32 s15, s14, 31
	s_lshl_b64 s[14:15], s[14:15], 12
	v_mul_f32_e32 v92, 0x45800000, v2
	v_cndmask_b32_e32 v2, v2, v92, vcc
	v_pk_mul_f32 v[88:89], v[88:89], v[2:3] op_sel_hi:[1,0]
	v_pk_mul_f32 v[86:87], v[86:87], v[2:3] op_sel_hi:[1,0]
	v_pk_fma_f32 v[88:89], v[54:55], v[88:89], v[90:91]
	v_pk_fma_f32 v[86:87], v[72:73], v[86:87], v[100:101]
	v_and_b32_sdwa v2, v89, v202 dst_sel:DWORD dst_unused:UNUSED_PAD src0_sel:WORD_1 src1_sel:DWORD
	v_and_b32_sdwa v94, v88, v202 dst_sel:DWORD dst_unused:UNUSED_PAD src0_sel:WORD_1 src1_sel:DWORD
	v_add3_u32 v88, v88, v94, s5
	v_add3_u32 v2, v89, v2, s5
	v_and_b32_sdwa v89, v87, v202 dst_sel:DWORD dst_unused:UNUSED_PAD src0_sel:WORD_1 src1_sel:DWORD
	v_and_b32_sdwa v94, v86, v202 dst_sel:DWORD dst_unused:UNUSED_PAD src0_sel:WORD_1 src1_sel:DWORD
	v_add3_u32 v87, v87, v89, s5
	v_add3_u32 v86, v86, v94, s5
	v_and_b32_e32 v87, 0xffff0000, v87
	v_and_b32_e32 v86, 0xffff0000, v86
	v_lshl_add_u64 v[92:93], v[28:29], 0, s[14:15]
	v_or_b32_sdwa v87, v87, v2 dst_sel:DWORD dst_unused:UNUSED_PAD src0_sel:DWORD src1_sel:WORD_1
	v_or_b32_sdwa v86, v86, v88 dst_sel:DWORD dst_unused:UNUSED_PAD src0_sel:DWORD src1_sel:WORD_1
	v_fma_f32 v2, s13, v206, v203
	global_store_dwordx2 v[92:93], v[86:87], off sc0 sc1
	v_cmp_gt_f32_e32 vcc, s2, v2
	v_mul_f32_e32 v86, 0x4b800000, v2
	s_add_i32 s14, s0, 4
	v_cndmask_b32_e32 v2, v2, v86, vcc
	v_rsq_f32_e32 v2, v2
	s_ashr_i32 s15, s14, 31
	s_lshl_b64 s[14:15], s[14:15], 12
	v_mul_f32_e32 v86, 0x45800000, v2
	v_cndmask_b32_e32 v2, v2, v86, vcc
	v_pk_mul_f32 v[84:85], v[84:85], v[2:3] op_sel_hi:[1,0]
	v_pk_mul_f32 v[82:83], v[82:83], v[2:3] op_sel_hi:[1,0]
	v_pk_fma_f32 v[84:85], v[54:55], v[84:85], v[90:91]
	v_pk_fma_f32 v[82:83], v[72:73], v[82:83], v[100:101]
	v_and_b32_sdwa v2, v85, v202 dst_sel:DWORD dst_unused:UNUSED_PAD src0_sel:WORD_1 src1_sel:DWORD
	v_and_b32_sdwa v88, v84, v202 dst_sel:DWORD dst_unused:UNUSED_PAD src0_sel:WORD_1 src1_sel:DWORD
	v_add3_u32 v84, v84, v88, s5
	v_add3_u32 v2, v85, v2, s5
	v_and_b32_sdwa v85, v83, v202 dst_sel:DWORD dst_unused:UNUSED_PAD src0_sel:WORD_1 src1_sel:DWORD
	v_and_b32_sdwa v88, v82, v202 dst_sel:DWORD dst_unused:UNUSED_PAD src0_sel:WORD_1 src1_sel:DWORD
	v_add3_u32 v83, v83, v85, s5
	v_add3_u32 v82, v82, v88, s5
	v_and_b32_e32 v83, 0xffff0000, v83
	v_and_b32_e32 v82, 0xffff0000, v82
	v_lshl_add_u64 v[86:87], v[28:29], 0, s[14:15]
	v_or_b32_sdwa v83, v83, v2 dst_sel:DWORD dst_unused:UNUSED_PAD src0_sel:DWORD src1_sel:WORD_1
	v_or_b32_sdwa v82, v82, v84 dst_sel:DWORD dst_unused:UNUSED_PAD src0_sel:DWORD src1_sel:WORD_1
	v_fma_f32 v2, s12, v206, v203
	global_store_dwordx2 v[86:87], v[82:83], off sc0 sc1
	v_cmp_gt_f32_e32 vcc, s2, v2
	v_mul_f32_e32 v82, 0x4b800000, v2
	s_add_i32 s12, s0, 5
	v_cndmask_b32_e32 v2, v2, v82, vcc
	v_rsq_f32_e32 v2, v2
	s_ashr_i32 s13, s12, 31
	s_lshl_b64 s[12:13], s[12:13], 12
	v_mul_f32_e32 v82, 0x45800000, v2
	v_cndmask_b32_e32 v2, v2, v82, vcc
	v_pk_mul_f32 v[80:81], v[80:81], v[2:3] op_sel_hi:[1,0]
	v_pk_mul_f32 v[78:79], v[78:79], v[2:3] op_sel_hi:[1,0]
	v_pk_fma_f32 v[80:81], v[54:55], v[80:81], v[90:91]
	v_pk_fma_f32 v[78:79], v[72:73], v[78:79], v[100:101]
	v_and_b32_sdwa v2, v81, v202 dst_sel:DWORD dst_unused:UNUSED_PAD src0_sel:WORD_1 src1_sel:DWORD
	v_and_b32_sdwa v84, v80, v202 dst_sel:DWORD dst_unused:UNUSED_PAD src0_sel:WORD_1 src1_sel:DWORD
	v_add3_u32 v80, v80, v84, s5
	v_add3_u32 v2, v81, v2, s5
	v_and_b32_sdwa v81, v79, v202 dst_sel:DWORD dst_unused:UNUSED_PAD src0_sel:WORD_1 src1_sel:DWORD
	v_and_b32_sdwa v84, v78, v202 dst_sel:DWORD dst_unused:UNUSED_PAD src0_sel:WORD_1 src1_sel:DWORD
	v_add3_u32 v79, v79, v81, s5
	v_add3_u32 v78, v78, v84, s5
	v_and_b32_e32 v79, 0xffff0000, v79
	v_and_b32_e32 v78, 0xffff0000, v78
	v_lshl_add_u64 v[82:83], v[28:29], 0, s[12:13]
	v_or_b32_sdwa v79, v79, v2 dst_sel:DWORD dst_unused:UNUSED_PAD src0_sel:DWORD src1_sel:WORD_1
	v_or_b32_sdwa v78, v78, v80 dst_sel:DWORD dst_unused:UNUSED_PAD src0_sel:DWORD src1_sel:WORD_1
	v_fma_f32 v2, s11, v206, v203
	global_store_dwordx2 v[82:83], v[78:79], off sc0 sc1
	v_cmp_gt_f32_e32 vcc, s2, v2
	v_mul_f32_e32 v78, 0x4b800000, v2
	s_add_i32 s12, s0, 6
	v_cndmask_b32_e32 v2, v2, v78, vcc
	v_rsq_f32_e32 v2, v2
	s_ashr_i32 s13, s12, 31
	s_lshl_b64 s[12:13], s[12:13], 12
	v_mul_f32_e32 v78, 0x45800000, v2
	v_cndmask_b32_e32 v2, v2, v78, vcc
	v_pk_mul_f32 v[76:77], v[76:77], v[2:3] op_sel_hi:[1,0]
	v_pk_mul_f32 v[74:75], v[74:75], v[2:3] op_sel_hi:[1,0]
	v_pk_fma_f32 v[76:77], v[54:55], v[76:77], v[90:91]
	v_pk_fma_f32 v[74:75], v[72:73], v[74:75], v[100:101]
	v_and_b32_sdwa v2, v77, v202 dst_sel:DWORD dst_unused:UNUSED_PAD src0_sel:WORD_1 src1_sel:DWORD
	v_and_b32_sdwa v80, v76, v202 dst_sel:DWORD dst_unused:UNUSED_PAD src0_sel:WORD_1 src1_sel:DWORD
	v_add3_u32 v76, v76, v80, s5
	v_add3_u32 v2, v77, v2, s5
	v_and_b32_sdwa v77, v75, v202 dst_sel:DWORD dst_unused:UNUSED_PAD src0_sel:WORD_1 src1_sel:DWORD
	v_and_b32_sdwa v80, v74, v202 dst_sel:DWORD dst_unused:UNUSED_PAD src0_sel:WORD_1 src1_sel:DWORD
	v_add3_u32 v75, v75, v77, s5
	v_add3_u32 v74, v74, v80, s5
	v_and_b32_e32 v75, 0xffff0000, v75
	v_and_b32_e32 v74, 0xffff0000, v74
	v_lshl_add_u64 v[78:79], v[28:29], 0, s[12:13]
	v_or_b32_sdwa v75, v75, v2 dst_sel:DWORD dst_unused:UNUSED_PAD src0_sel:DWORD src1_sel:WORD_1
	v_or_b32_sdwa v74, v74, v76 dst_sel:DWORD dst_unused:UNUSED_PAD src0_sel:DWORD src1_sel:WORD_1
	v_fma_f32 v2, s10, v206, v203
	global_store_dwordx2 v[78:79], v[74:75], off sc0 sc1
	v_cmp_gt_f32_e32 vcc, s2, v2
	v_mul_f32_e32 v74, 0x4b800000, v2
	s_add_i32 s10, s0, 7
	v_cndmask_b32_e32 v2, v2, v74, vcc
	v_rsq_f32_e32 v2, v2
	s_ashr_i32 s11, s10, 31
	s_lshl_b64 s[10:11], s[10:11], 12
	v_mul_f32_e32 v74, 0x45800000, v2
	v_cndmask_b32_e32 v2, v2, v74, vcc
	v_pk_mul_f32 v[14:15], v[14:15], v[2:3] op_sel_hi:[1,0]
	v_pk_mul_f32 v[12:13], v[12:13], v[2:3] op_sel_hi:[1,0]
	v_pk_fma_f32 v[14:15], v[54:55], v[14:15], v[90:91]
	v_pk_fma_f32 v[12:13], v[72:73], v[12:13], v[100:101]
	v_and_b32_sdwa v2, v15, v202 dst_sel:DWORD dst_unused:UNUSED_PAD src0_sel:WORD_1 src1_sel:DWORD
	v_and_b32_sdwa v76, v14, v202 dst_sel:DWORD dst_unused:UNUSED_PAD src0_sel:WORD_1 src1_sel:DWORD
	v_add3_u32 v14, v14, v76, s5
	v_add3_u32 v2, v15, v2, s5
	v_and_b32_sdwa v15, v13, v202 dst_sel:DWORD dst_unused:UNUSED_PAD src0_sel:WORD_1 src1_sel:DWORD
	v_and_b32_sdwa v76, v12, v202 dst_sel:DWORD dst_unused:UNUSED_PAD src0_sel:WORD_1 src1_sel:DWORD
	v_add3_u32 v13, v13, v15, s5
	v_add3_u32 v12, v12, v76, s5
	v_and_b32_e32 v13, 0xffff0000, v13
	v_and_b32_e32 v12, 0xffff0000, v12
	v_lshl_add_u64 v[74:75], v[28:29], 0, s[10:11]
	v_or_b32_sdwa v13, v13, v2 dst_sel:DWORD dst_unused:UNUSED_PAD src0_sel:DWORD src1_sel:WORD_1
	v_or_b32_sdwa v12, v12, v14 dst_sel:DWORD dst_unused:UNUSED_PAD src0_sel:DWORD src1_sel:WORD_1
	global_store_dwordx2 v[74:75], v[12:13], off sc0 sc1

.LBB0_1367:
	s_or_b64 exec, exec, s[10:11]
	v_lshl_add_u32 v2, v1, 2, s12
	v_lshlrev_b32_e32 v124, 16, v74
	v_and_b32_e32 v126, 0xffff0000, v74
	s_waitcnt lgkmcnt(0)
	s_barrier
	ds_read_b32 v74, v2
	v_lshlrev_b32_e32 v125, 16, v75
	v_and_b32_e32 v127, 0xffff0000, v75
	s_mov_b32 s2, 0x800000
	v_and_b32_e32 v137, 0xffff0000, v89
	s_waitcnt lgkmcnt(0)
	ds_bpermute_b32 v75, v141, v74
	v_and_b32_e32 v136, 0xffff0000, v88
	v_lshlrev_b32_e32 v129, 16, v77
	v_lshlrev_b32_e32 v128, 16, v76
	v_and_b32_e32 v131, 0xffff0000, v77
	s_waitcnt lgkmcnt(0)
	v_add_f32_e32 v74, v74, v75
	ds_bpermute_b32 v75, v142, v74
	v_and_b32_e32 v130, 0xffff0000, v76
	v_lshlrev_b32_e32 v99, 16, v89
	v_lshlrev_b32_e32 v98, 16, v88
	v_and_b32_e32 v97, 0xffff0000, v87
	s_waitcnt lgkmcnt(0)
	v_add_f32_e32 v74, v74, v75
	ds_bpermute_b32 v75, v143, v74
	v_and_b32_e32 v96, 0xffff0000, v86
	v_lshlrev_b32_e32 v95, 16, v87
	v_lshlrev_b32_e32 v94, 16, v86
	v_and_b32_e32 v135, 0xffff0000, v85
	s_waitcnt lgkmcnt(0)
	v_add_f32_e32 v74, v74, v75
	v_and_b32_e32 v134, 0xffff0000, v84
	v_readlane_b32 s14, v74, 0
	v_readlane_b32 s15, v74, 1
	v_readlane_b32 s16, v74, 2
	v_readlane_b32 s17, v74, 3
	v_readlane_b32 s13, v74, 4
	v_readlane_b32 s11, v74, 5
	v_readlane_b32 s10, v74, 6
	v_readlane_b32 s1, v74, 7
	v_fma_f32 v74, s14, v206, v203
	v_cmp_gt_f32_e32 vcc, s2, v74
	v_mul_f32_e32 v75, 0x4b800000, v74
	v_lshlrev_b32_e32 v89, 16, v85
	v_cndmask_b32_e32 v74, v74, v75, vcc
	v_rsq_f32_e32 v74, v74
	v_lshlrev_b32_e32 v88, 16, v84
	v_and_b32_e32 v87, 0xffff0000, v83
	v_and_b32_e32 v86, 0xffff0000, v82
	v_mul_f32_e32 v75, 0x45800000, v74
	v_cndmask_b32_e32 v74, v74, v75, vcc
	v_pk_mul_f32 v[76:77], v[112:113], v[74:75] op_sel_hi:[1,0]
	v_pk_mul_f32 v[74:75], v[110:111], v[74:75] op_sel_hi:[1,0]
	v_pk_fma_f32 v[112:113], v[8:9], v[76:77], v[98:99]
	v_pk_fma_f32 v[110:111], v[10:11], v[74:75], v[136:137]
	v_fma_f32 v74, s15, v206, v203
	v_cmp_gt_f32_e32 vcc, s2, v74
	v_mul_f32_e32 v75, 0x4b800000, v74
	v_lshlrev_b32_e32 v85, 16, v83
	v_cndmask_b32_e32 v74, v74, v75, vcc
	v_rsq_f32_e32 v74, v74
	v_lshlrev_b32_e32 v84, 16, v82
	v_lshlrev_b32_e32 v83, 16, v81
	v_lshlrev_b32_e32 v82, 16, v80
	v_mul_f32_e32 v75, 0x45800000, v74
	v_cndmask_b32_e32 v74, v74, v75, vcc
	v_pk_mul_f32 v[76:77], v[122:123], v[74:75] op_sel_hi:[1,0]
	v_pk_mul_f32 v[74:75], v[114:115], v[74:75] op_sel_hi:[1,0]
	v_pk_fma_f32 v[98:99], v[8:9], v[76:77], v[94:95]
	v_pk_fma_f32 v[96:97], v[10:11], v[74:75], v[96:97]
	v_fma_f32 v74, s16, v206, v203
	v_cmp_gt_f32_e32 vcc, s2, v74
	v_mul_f32_e32 v75, 0x4b800000, v74
	v_and_b32_e32 v133, 0xffff0000, v81
	v_cndmask_b32_e32 v74, v74, v75, vcc
	v_rsq_f32_e32 v74, v74
	v_and_b32_e32 v132, 0xffff0000, v80
	v_lshlrev_b32_e32 v81, 16, v79
	v_lshlrev_b32_e32 v80, 16, v78
	v_mul_f32_e32 v75, 0x45800000, v74
	v_cndmask_b32_e32 v74, v74, v75, vcc
	v_pk_mul_f32 v[76:77], v[120:121], v[74:75] op_sel_hi:[1,0]
	v_pk_mul_f32 v[74:75], v[92:93], v[74:75] op_sel_hi:[1,0]
	v_pk_fma_f32 v[94:95], v[8:9], v[76:77], v[88:89]
	v_pk_fma_f32 v[92:93], v[10:11], v[74:75], v[134:135]
	v_fma_f32 v74, s17, v206, v203
	v_cmp_gt_f32_e32 vcc, s2, v74
	v_mul_f32_e32 v75, 0x4b800000, v74
	v_and_b32_e32 v79, 0xffff0000, v79
	v_cndmask_b32_e32 v74, v74, v75, vcc
	v_rsq_f32_e32 v74, v74
	v_and_b32_e32 v78, 0xffff0000, v78
	v_mul_f32_e32 v75, 0x45800000, v74
	v_cndmask_b32_e32 v74, v74, v75, vcc
	v_pk_mul_f32 v[76:77], v[118:119], v[74:75] op_sel_hi:[1,0]
	v_pk_mul_f32 v[74:75], v[106:107], v[74:75] op_sel_hi:[1,0]
	v_pk_fma_f32 v[88:89], v[8:9], v[76:77], v[84:85]
	v_pk_fma_f32 v[86:87], v[10:11], v[74:75], v[86:87]
	v_fma_f32 v74, s13, v206, v203
	v_cmp_gt_f32_e32 vcc, s2, v74
	v_mul_f32_e32 v75, 0x4b800000, v74
	s_nop 0
	v_cndmask_b32_e32 v74, v74, v75, vcc
	v_rsq_f32_e32 v74, v74
	s_nop 0
	v_mul_f32_e32 v75, 0x45800000, v74
	v_cndmask_b32_e32 v74, v74, v75, vcc
	v_pk_mul_f32 v[76:77], v[116:117], v[74:75] op_sel_hi:[1,0]
	v_pk_mul_f32 v[74:75], v[102:103], v[74:75] op_sel_hi:[1,0]
	v_pk_fma_f32 v[84:85], v[8:9], v[76:77], v[82:83]
	v_pk_fma_f32 v[82:83], v[10:11], v[74:75], v[132:133]
	v_fma_f32 v74, s11, v206, v203
	v_cmp_gt_f32_e32 vcc, s2, v74
	v_mul_f32_e32 v75, 0x4b800000, v74
	s_nop 0
	v_cndmask_b32_e32 v74, v74, v75, vcc
	v_rsq_f32_e32 v74, v74
	s_nop 0
	v_mul_f32_e32 v75, 0x45800000, v74
	v_cndmask_b32_e32 v74, v74, v75, vcc
	v_pk_mul_f32 v[76:77], v[108:109], v[74:75] op_sel_hi:[1,0]
	v_pk_mul_f32 v[74:75], v[100:101], v[74:75] op_sel_hi:[1,0]
	v_pk_fma_f32 v[80:81], v[8:9], v[76:77], v[80:81]
	v_pk_fma_f32 v[78:79], v[10:11], v[74:75], v[78:79]
	v_fma_f32 v74, s10, v206, v203
	v_cmp_gt_f32_e32 vcc, s2, v74
	v_mul_f32_e32 v75, 0x4b800000, v74
	s_mov_b64 s[10:11], -1
	v_cndmask_b32_e32 v74, v74, v75, vcc
	v_rsq_f32_e32 v74, v74
	s_nop 0
	v_mul_f32_e32 v75, 0x45800000, v74
	v_cndmask_b32_e32 v74, v74, v75, vcc
	v_pk_mul_f32 v[14:15], v[14:15], v[74:75] op_sel_hi:[1,0]
	v_pk_mul_f32 v[76:77], v[104:105], v[74:75] op_sel_hi:[1,0]
	v_pk_fma_f32 v[74:75], v[10:11], v[14:15], v[130:131]
	v_fma_f32 v14, s1, v206, v203
	v_cmp_gt_f32_e32 vcc, s2, v14
	v_mul_f32_e32 v15, 0x4b800000, v14
	v_pk_fma_f32 v[76:77], v[8:9], v[76:77], v[128:129]
	v_cndmask_b32_e32 v14, v14, v15, vcc
	v_rsq_f32_e32 v14, v14
	s_nop 0
	v_mul_f32_e32 v15, 0x45800000, v14
	v_cndmask_b32_e32 v14, v14, v15, vcc
	v_pk_mul_f32 v[90:91], v[90:91], v[14:15] op_sel_hi:[1,0]
	v_pk_mul_f32 v[12:13], v[12:13], v[14:15] op_sel_hi:[1,0]
	v_pk_fma_f32 v[14:15], v[8:9], v[90:91], v[124:125]
	v_pk_fma_f32 v[12:13], v[10:11], v[12:13], v[126:127]
	s_and_b64 vcc, exec, s[44:45]
	s_cbranch_vccnz .LBB0_1370
	v_and_b32_sdwa v101, v112, v202 dst_sel:DWORD dst_unused:UNUSED_PAD src0_sel:WORD_1 src1_sel:DWORD
	v_add3_u32 v102, v112, v101, s5
	v_and_b32_sdwa v101, v111, v202 dst_sel:DWORD dst_unused:UNUSED_PAD src0_sel:WORD_1 src1_sel:DWORD
	v_and_b32_sdwa v103, v110, v202 dst_sel:DWORD dst_unused:UNUSED_PAD src0_sel:WORD_1 src1_sel:DWORD
	s_ashr_i32 s1, s0, 31
	v_and_b32_sdwa v100, v113, v202 dst_sel:DWORD dst_unused:UNUSED_PAD src0_sel:WORD_1 src1_sel:DWORD
	v_add3_u32 v101, v111, v101, s5
	v_add3_u32 v103, v110, v103, s5
	s_lshl_b64 s[10:11], s[0:1], 12
	v_add3_u32 v100, v113, v100, s5
	v_and_b32_e32 v101, 0xffff0000, v101
	v_and_b32_e32 v103, 0xffff0000, v103
	v_lshl_add_u64 v[90:91], v[24:25], 0, s[10:11]
	v_or_b32_sdwa v101, v101, v100 dst_sel:DWORD dst_unused:UNUSED_PAD src0_sel:DWORD src1_sel:WORD_1
	v_or_b32_sdwa v100, v103, v102 dst_sel:DWORD dst_unused:UNUSED_PAD src0_sel:DWORD src1_sel:WORD_1
	global_store_dwordx2 v[90:91], v[100:101], off sc0 sc1
	v_and_b32_sdwa v101, v98, v202 dst_sel:DWORD dst_unused:UNUSED_PAD src0_sel:WORD_1 src1_sel:DWORD
	s_add_i32 s10, s0, 1
	v_add3_u32 v102, v98, v101, s5
	v_and_b32_sdwa v101, v97, v202 dst_sel:DWORD dst_unused:UNUSED_PAD src0_sel:WORD_1 src1_sel:DWORD
	v_and_b32_sdwa v103, v96, v202 dst_sel:DWORD dst_unused:UNUSED_PAD src0_sel:WORD_1 src1_sel:DWORD
	s_ashr_i32 s11, s10, 31
	v_and_b32_sdwa v100, v99, v202 dst_sel:DWORD dst_unused:UNUSED_PAD src0_sel:WORD_1 src1_sel:DWORD
	v_add3_u32 v101, v97, v101, s5
	v_add3_u32 v103, v96, v103, s5
	s_lshl_b64 s[10:11], s[10:11], 12
	v_add3_u32 v100, v99, v100, s5
	v_and_b32_e32 v101, 0xffff0000, v101
	v_and_b32_e32 v103, 0xffff0000, v103
	v_lshl_add_u64 v[90:91], v[24:25], 0, s[10:11]
	v_or_b32_sdwa v101, v101, v100 dst_sel:DWORD dst_unused:UNUSED_PAD src0_sel:DWORD src1_sel:WORD_1
	v_or_b32_sdwa v100, v103, v102 dst_sel:DWORD dst_unused:UNUSED_PAD src0_sel:DWORD src1_sel:WORD_1
	global_store_dwordx2 v[90:91], v[100:101], off sc0 sc1
	v_and_b32_sdwa v101, v94, v202 dst_sel:DWORD dst_unused:UNUSED_PAD src0_sel:WORD_1 src1_sel:DWORD
	s_add_i32 s10, s0, 2
	v_add3_u32 v102, v94, v101, s5
	v_and_b32_sdwa v101, v93, v202 dst_sel:DWORD dst_unused:UNUSED_PAD src0_sel:WORD_1 src1_sel:DWORD
	v_and_b32_sdwa v103, v92, v202 dst_sel:DWORD dst_unused:UNUSED_PAD src0_sel:WORD_1 src1_sel:DWORD
	s_ashr_i32 s11, s10, 31
	v_and_b32_sdwa v100, v95, v202 dst_sel:DWORD dst_unused:UNUSED_PAD src0_sel:WORD_1 src1_sel:DWORD
	v_add3_u32 v101, v93, v101, s5
	v_add3_u32 v103, v92, v103, s5
	s_lshl_b64 s[10:11], s[10:11], 12
	v_add3_u32 v100, v95, v100, s5
	v_and_b32_e32 v101, 0xffff0000, v101
	v_and_b32_e32 v103, 0xffff0000, v103
	v_lshl_add_u64 v[90:91], v[24:25], 0, s[10:11]
	v_or_b32_sdwa v101, v101, v100 dst_sel:DWORD dst_unused:UNUSED_PAD src0_sel:DWORD src1_sel:WORD_1
	v_or_b32_sdwa v100, v103, v102 dst_sel:DWORD dst_unused:UNUSED_PAD src0_sel:DWORD src1_sel:WORD_1
	global_store_dwordx2 v[90:91], v[100:101], off sc0 sc1
	v_and_b32_sdwa v101, v88, v202 dst_sel:DWORD dst_unused:UNUSED_PAD src0_sel:WORD_1 src1_sel:DWORD
	s_add_i32 s10, s0, 3
	v_add3_u32 v102, v88, v101, s5
	v_and_b32_sdwa v101, v87, v202 dst_sel:DWORD dst_unused:UNUSED_PAD src0_sel:WORD_1 src1_sel:DWORD
	v_and_b32_sdwa v103, v86, v202 dst_sel:DWORD dst_unused:UNUSED_PAD src0_sel:WORD_1 src1_sel:DWORD
	s_ashr_i32 s11, s10, 31
	v_and_b32_sdwa v100, v89, v202 dst_sel:DWORD dst_unused:UNUSED_PAD src0_sel:WORD_1 src1_sel:DWORD
	v_add3_u32 v101, v87, v101, s5
	v_add3_u32 v103, v86, v103, s5
	s_lshl_b64 s[10:11], s[10:11], 12
	v_add3_u32 v100, v89, v100, s5
	v_and_b32_e32 v101, 0xffff0000, v101
	v_and_b32_e32 v103, 0xffff0000, v103
	v_lshl_add_u64 v[90:91], v[24:25], 0, s[10:11]
	v_or_b32_sdwa v101, v101, v100 dst_sel:DWORD dst_unused:UNUSED_PAD src0_sel:DWORD src1_sel:WORD_1
	v_or_b32_sdwa v100, v103, v102 dst_sel:DWORD dst_unused:UNUSED_PAD src0_sel:DWORD src1_sel:WORD_1
	global_store_dwordx2 v[90:91], v[100:101], off sc0 sc1
	v_and_b32_sdwa v101, v84, v202 dst_sel:DWORD dst_unused:UNUSED_PAD src0_sel:WORD_1 src1_sel:DWORD
	s_add_i32 s10, s0, 4
	v_add3_u32 v102, v84, v101, s5
	v_and_b32_sdwa v101, v83, v202 dst_sel:DWORD dst_unused:UNUSED_PAD src0_sel:WORD_1 src1_sel:DWORD
	v_and_b32_sdwa v103, v82, v202 dst_sel:DWORD dst_unused:UNUSED_PAD src0_sel:WORD_1 src1_sel:DWORD
	s_ashr_i32 s11, s10, 31
	v_and_b32_sdwa v100, v85, v202 dst_sel:DWORD dst_unused:UNUSED_PAD src0_sel:WORD_1 src1_sel:DWORD
	v_add3_u32 v101, v83, v101, s5
	v_add3_u32 v103, v82, v103, s5
	s_lshl_b64 s[10:11], s[10:11], 12
	v_add3_u32 v100, v85, v100, s5
	v_and_b32_e32 v101, 0xffff0000, v101
	v_and_b32_e32 v103, 0xffff0000, v103
	v_lshl_add_u64 v[90:91], v[24:25], 0, s[10:11]
	v_or_b32_sdwa v101, v101, v100 dst_sel:DWORD dst_unused:UNUSED_PAD src0_sel:DWORD src1_sel:WORD_1
	v_or_b32_sdwa v100, v103, v102 dst_sel:DWORD dst_unused:UNUSED_PAD src0_sel:DWORD src1_sel:WORD_1
	global_store_dwordx2 v[90:91], v[100:101], off sc0 sc1
	v_and_b32_sdwa v101, v80, v202 dst_sel:DWORD dst_unused:UNUSED_PAD src0_sel:WORD_1 src1_sel:DWORD
	s_add_i32 s10, s0, 5
	v_add3_u32 v102, v80, v101, s5
	v_and_b32_sdwa v101, v79, v202 dst_sel:DWORD dst_unused:UNUSED_PAD src0_sel:WORD_1 src1_sel:DWORD
	v_and_b32_sdwa v103, v78, v202 dst_sel:DWORD dst_unused:UNUSED_PAD src0_sel:WORD_1 src1_sel:DWORD
	s_ashr_i32 s11, s10, 31
	v_and_b32_sdwa v100, v81, v202 dst_sel:DWORD dst_unused:UNUSED_PAD src0_sel:WORD_1 src1_sel:DWORD
	v_add3_u32 v101, v79, v101, s5
	v_add3_u32 v103, v78, v103, s5
	s_lshl_b64 s[10:11], s[10:11], 12
	v_add3_u32 v100, v81, v100, s5
	v_and_b32_e32 v101, 0xffff0000, v101
	v_and_b32_e32 v103, 0xffff0000, v103
	v_lshl_add_u64 v[90:91], v[24:25], 0, s[10:11]
	v_or_b32_sdwa v101, v101, v100 dst_sel:DWORD dst_unused:UNUSED_PAD src0_sel:DWORD src1_sel:WORD_1
	v_or_b32_sdwa v100, v103, v102 dst_sel:DWORD dst_unused:UNUSED_PAD src0_sel:DWORD src1_sel:WORD_1
	global_store_dwordx2 v[90:91], v[100:101], off sc0 sc1
	v_and_b32_sdwa v101, v76, v202 dst_sel:DWORD dst_unused:UNUSED_PAD src0_sel:WORD_1 src1_sel:DWORD
	s_add_i32 s10, s0, 6
	v_add3_u32 v102, v76, v101, s5
	v_and_b32_sdwa v101, v75, v202 dst_sel:DWORD dst_unused:UNUSED_PAD src0_sel:WORD_1 src1_sel:DWORD
	v_and_b32_sdwa v103, v74, v202 dst_sel:DWORD dst_unused:UNUSED_PAD src0_sel:WORD_1 src1_sel:DWORD
	s_ashr_i32 s11, s10, 31
	v_and_b32_sdwa v100, v77, v202 dst_sel:DWORD dst_unused:UNUSED_PAD src0_sel:WORD_1 src1_sel:DWORD
	v_add3_u32 v101, v75, v101, s5
	v_add3_u32 v103, v74, v103, s5
	s_lshl_b64 s[10:11], s[10:11], 12
	v_add3_u32 v100, v77, v100, s5
	v_and_b32_e32 v101, 0xffff0000, v101
	v_and_b32_e32 v103, 0xffff0000, v103
	v_lshl_add_u64 v[90:91], v[24:25], 0, s[10:11]
	v_or_b32_sdwa v101, v101, v100 dst_sel:DWORD dst_unused:UNUSED_PAD src0_sel:DWORD src1_sel:WORD_1
	v_or_b32_sdwa v100, v103, v102 dst_sel:DWORD dst_unused:UNUSED_PAD src0_sel:DWORD src1_sel:WORD_1
	global_store_dwordx2 v[90:91], v[100:101], off sc0 sc1
	v_and_b32_sdwa v101, v14, v202 dst_sel:DWORD dst_unused:UNUSED_PAD src0_sel:WORD_1 src1_sel:DWORD
	s_add_i32 s10, s0, 7
	v_add3_u32 v102, v14, v101, s5
	v_and_b32_sdwa v101, v13, v202 dst_sel:DWORD dst_unused:UNUSED_PAD src0_sel:WORD_1 src1_sel:DWORD
	v_and_b32_sdwa v103, v12, v202 dst_sel:DWORD dst_unused:UNUSED_PAD src0_sel:WORD_1 src1_sel:DWORD
	s_ashr_i32 s11, s10, 31
	v_and_b32_sdwa v100, v15, v202 dst_sel:DWORD dst_unused:UNUSED_PAD src0_sel:WORD_1 src1_sel:DWORD
	v_add3_u32 v101, v13, v101, s5
	v_add3_u32 v103, v12, v103, s5
	s_lshl_b64 s[10:11], s[10:11], 12
	v_add3_u32 v100, v15, v100, s5
	v_and_b32_e32 v101, 0xffff0000, v101
	v_and_b32_e32 v103, 0xffff0000, v103
	v_lshl_add_u64 v[90:91], v[24:25], 0, s[10:11]
	v_or_b32_sdwa v101, v101, v100 dst_sel:DWORD dst_unused:UNUSED_PAD src0_sel:DWORD src1_sel:WORD_1
	v_or_b32_sdwa v100, v103, v102 dst_sel:DWORD dst_unused:UNUSED_PAD src0_sel:DWORD src1_sel:WORD_1
	global_store_dwordx2 v[90:91], v[100:101], off sc0 sc1
	s_cbranch_execz .LBB0_1371

.LBB0_1371:
	s_ashr_i32 s1, s0, 31
	s_lshl_b64 s[10:11], s[0:1], 13
	v_lshl_add_u64 v[90:91], v[36:37], 0, s[10:11]
	v_mov_b32_e32 v100, v112
	v_mov_b32_e32 v101, v110
	v_mov_b32_e32 v102, v113
	v_mov_b32_e32 v103, v111
	v_add_co_u32_e32 v104, vcc, 0x2000, v90
	global_store_dwordx4 v[90:91], v[100:103], off sc0 sc1
	s_nop 0
	v_addc_co_u32_e32 v105, vcc, 0, v91, vcc
	v_mov_b32_e32 v100, v98
	v_mov_b32_e32 v101, v96
	v_mov_b32_e32 v102, v99
	v_mov_b32_e32 v103, v97
	global_store_dwordx4 v[104:105], v[100:103], off sc0 sc1
	v_add_co_u32_e32 v104, vcc, 0x4000, v90
	s_nop 0
	v_mov_b32_e32 v100, v94
	v_mov_b32_e32 v101, v92
	v_mov_b32_e32 v102, v95
	v_mov_b32_e32 v103, v93
	v_addc_co_u32_e32 v105, vcc, 0, v91, vcc
	global_store_dwordx4 v[104:105], v[100:103], off sc0 sc1
	v_add_co_u32_e32 v104, vcc, 0x6000, v90
	s_nop 0
	v_mov_b32_e32 v100, v88
	v_mov_b32_e32 v101, v86
	v_mov_b32_e32 v102, v89
	v_mov_b32_e32 v103, v87
	v_addc_co_u32_e32 v105, vcc, 0, v91, vcc
	global_store_dwordx4 v[104:105], v[100:103], off sc0 sc1
	v_add_co_u32_e32 v104, vcc, 0x8000, v90
	s_nop 0
	v_mov_b32_e32 v100, v84
	v_mov_b32_e32 v101, v82
	v_mov_b32_e32 v102, v85
	v_mov_b32_e32 v103, v83
	v_addc_co_u32_e32 v105, vcc, 0, v91, vcc
	global_store_dwordx4 v[104:105], v[100:103], off sc0 sc1
	v_add_co_u32_e32 v104, vcc, 0xa000, v90
	s_nop 0
	v_mov_b32_e32 v100, v80
	v_mov_b32_e32 v101, v78
	v_mov_b32_e32 v102, v81
	v_mov_b32_e32 v103, v79
	v_addc_co_u32_e32 v105, vcc, 0, v91, vcc
	global_store_dwordx4 v[104:105], v[100:103], off sc0 sc1
	v_add_co_u32_e32 v104, vcc, 0xc000, v90
	s_nop 0
	v_mov_b32_e32 v100, v76
	v_addc_co_u32_e32 v105, vcc, 0, v91, vcc
	v_mov_b32_e32 v101, v74
	v_mov_b32_e32 v102, v77
	v_mov_b32_e32 v103, v75
	v_add_co_u32_e32 v90, vcc, 0xe000, v90
	global_store_dwordx4 v[104:105], v[100:103], off sc0 sc1
	s_nop 0
	v_addc_co_u32_e32 v91, vcc, 0, v91, vcc
	v_mov_b32_e32 v100, v14
	v_mov_b32_e32 v101, v12
	v_mov_b32_e32 v102, v15
	v_mov_b32_e32 v103, v13
	global_store_dwordx4 v[90:91], v[100:103], off sc0 sc1
	s_and_b64 vcc, exec, s[44:45]
	s_cbranch_vccnz .LBB0_1356
